# EpiResid GEMM epilogues (out-proj, memO, FFN2): 32 serialized residual loads per tile become two 16-load bursts into dead A/B fragment VGPRs with counted vmcnt
# speedup vs baseline: 1.1581x; 1.0105x over previous
; DI void st_bf16x4(bf16_t* p, f32x4 v) { u32x2 o; o.x = pk2e(v[0], v[1]); o.y = pk2e(v[2], v[3]); *(u32x2*)p = o; }
;   DI float operator()(int row, int colbase, int fq, f32x4 v0, f32x4 v1) const { one(row, colbase + 4 * fq, v0); one(row, colbase + 16 + 4 * fq, v1); return 0.f; }
;   DI float operator()(int row, int colbase, int fq, f32x4 v0, f32x4 v1) const { one(row, colbase + 4 * fq, v0); one(row, colbase + 16 + 4 * fq, v1); return 0.f; }
;   DI float operator()(int row, int colbase, int fq, f32x4 v0, f32x4 v1) const { one(row, colbase + 4 * fq, v0); one(row, colbase + 16 + 4 * fq, v1); return 0.f; }
;   DI float operator()(int row, int colbase, int fq, f32x4 v0, f32x4 v1) const { one(row, colbase + 4 * fq, v0); one(row, colbase + 16 + 4 * fq, v1); return 0.f; }
;     ...
; #pragma unroll
;     for (int ai = 0; ai < 2; ++ai)
; #pragma unroll
;       for (int m = 0; m < 4; ++m) {
;         const int row = brow + ai * HALF + wr * 64 + m * 16 + fr_e;
;         const float rsc = epi.rowscale(row);
;         float ssq = 0.f;
; #pragma unroll
;         for (int bj = 0; bj < 2; ++bj)
;           ssq += epi(row, bcol + bj * HALF + wc * 32, fq_e, acc[ai][bj][m][0] * rsc, acc[ai][bj][m][1] * rsc);
;         rowss[ai][m] = ssq;
;         __builtin_amdgcn_sched_barrier(0);
;       }
;   DI float operator()(int row, int colbase, int fq, f32x4 v0, f32x4 v1) const {
;     const size_t o = (size_t)row * D_ + colbase + 4 * fq;
;     const f32x4 a = *(const f32x4*)(src + o) + v0, b = *(const f32x4*)(src + o + 16) + v1;
;     *(f32x4*)(dst + o) = a; *(f32x4*)(dst + o + 16) = b;
;     if (xb) { st_bf16x4(xb + o, a); st_bf16x4(xb + o + 16, b); }
;     return ((a[0] * a[0] + a[1] * a[1]) + (a[2] * a[2] + a[3] * a[3])) + ((b[0] * b[0] + b[1] * b[1]) + (b[2] * b[2] + b[3] * b[3]));
.LBB0_47:
	v_mov_b32_e32 v134, v199
	s_add_i32 s1, s14, s34
	v_and_b32_e32 v141, 15, v134
	v_bfe_u32 v142, v134, 4, 2
	v_or_b32_e32 v134, s1, v141
	v_ashrrev_i32_e32 v135, 31, v134
	s_or_b32 s16, s0, s35
	v_lshlrev_b32_e32 v143, 2, v142
	v_lshlrev_b64 v[136:137], 11, v[134:135]
	v_or_b32_e32 v136, v136, v143
	s_ashr_i32 s17, s16, 31
	v_readlane_b32 s0, v253, 50
	v_lshl_add_u64 v[138:139], v[136:137], 0, s[16:17]
	v_readlane_b32 s1, v253, 51
	v_cndmask_b32_e64 v135, 0, 1, s[10:11]
	s_andn2_b64 vcc, exec, s[10:11]
	v_lshl_add_u64 v[148:149], v[138:139], 2, s[0:1]
	v_mov_b32_e32 v224, v148
	v_mov_b32_e32 v225, v149
	s_mov_b64 s[100:101], 0x20000
	global_load_dwordx4 v[152:155], v[224:225], off
	global_load_dwordx4 v[156:159], v[224:225], off offset:64
	global_load_dwordx4 v[160:163], v[224:225], off offset:512
	global_load_dwordx4 v[164:167], v[224:225], off offset:576
	v_lshl_add_u64 v[224:225], v[224:225], 0, s[100:101]
	global_load_dwordx4 v[168:171], v[224:225], off
	global_load_dwordx4 v[172:175], v[224:225], off offset:64
	global_load_dwordx4 v[176:179], v[224:225], off offset:512
	global_load_dwordx4 v[180:183], v[224:225], off offset:576
	v_lshl_add_u64 v[224:225], v[224:225], 0, s[100:101]
	global_load_dwordx4 v[184:187], v[224:225], off
	global_load_dwordx4 v[188:191], v[224:225], off offset:64
	global_load_dwordx4 v[200:203], v[224:225], off offset:512
	global_load_dwordx4 v[204:207], v[224:225], off offset:576
	v_lshl_add_u64 v[224:225], v[224:225], 0, s[100:101]
	global_load_dwordx4 v[208:211], v[224:225], off
	global_load_dwordx4 v[212:215], v[224:225], off offset:64
	global_load_dwordx4 v[216:219], v[224:225], off offset:512
	global_load_dwordx4 v[220:223], v[224:225], off offset:576
	v_cmp_ne_u32_e64 s[0:1], 1, v135
	s_waitcnt vmcnt(14)
	v_pk_add_f32 v[4:5], v[4:5], v[154:155]
	v_pk_add_f32 v[2:3], v[2:3], v[152:153]
	s_waitcnt vmcnt(14)
	v_pk_add_f32 v[8:9], v[8:9], v[158:159]
	v_pk_add_f32 v[6:7], v[6:7], v[156:157]
	global_store_dwordx4 v[148:149], v[2:5], off
	global_store_dwordx4 v[148:149], v[6:9], off offset:64
	s_cbranch_vccnz .LBB0_49
	v_readlane_b32 s18, v253, 54
	v_readlane_b32 s19, v253, 55
	v_cvt_pk_bf16_f32 v144, v2, v3
	v_cvt_pk_bf16_f32 v145, v4, v5
	v_lshl_add_u64 v[138:139], v[138:139], 1, s[18:19]
	global_store_dwordx2 v[138:139], v[144:145], off
	v_cvt_pk_bf16_f32 v144, v6, v7
	v_cvt_pk_bf16_f32 v145, v8, v9
	global_store_dwordx2 v[138:139], v[144:145], off offset:32
.LBB0_49:
	s_or_b32 s18, s16, 0x80
	s_ashr_i32 s19, s18, 31
	v_readlane_b32 s20, v253, 50
	v_lshl_add_u64 v[136:137], v[136:137], 0, s[18:19]
	v_readlane_b32 s21, v253, 51
	s_and_b64 vcc, exec, s[0:1]
	s_nop 0
	v_lshl_add_u64 v[138:139], v[136:137], 2, s[20:21]
	s_waitcnt vmcnt(14)
	v_pk_add_f32 v[20:21], v[20:21], v[162:163]
	v_pk_add_f32 v[18:19], v[18:19], v[160:161]
	s_waitcnt vmcnt(14)
	v_pk_add_f32 v[24:25], v[24:25], v[166:167]
	v_pk_add_f32 v[22:23], v[22:23], v[164:165]
	global_store_dwordx4 v[138:139], v[18:21], off
	global_store_dwordx4 v[138:139], v[22:25], off offset:64
	s_cbranch_vccnz .LBB0_51
	v_readlane_b32 s20, v253, 54
	v_readlane_b32 s21, v253, 55
	v_cvt_pk_bf16_f32 v138, v18, v19
	v_cvt_pk_bf16_f32 v139, v20, v21
	v_lshl_add_u64 v[136:137], v[136:137], 1, s[20:21]
	global_store_dwordx2 v[136:137], v[138:139], off
	v_cvt_pk_bf16_f32 v138, v22, v23
	v_cvt_pk_bf16_f32 v139, v24, v25
	global_store_dwordx2 v[136:137], v[138:139], off offset:32
.LBB0_51:
	v_or_b32_e32 v136, 16, v134
	v_ashrrev_i32_e32 v137, 31, v136
	v_lshlrev_b64 v[136:137], 11, v[136:137]
	v_or_b32_e32 v136, v136, v143
	v_readlane_b32 s20, v253, 50
	v_lshl_add_u64 v[138:139], v[136:137], 0, s[16:17]
	v_readlane_b32 s21, v253, 51
	s_and_b64 vcc, exec, s[0:1]
	s_nop 0
	v_lshl_add_u64 v[148:149], v[138:139], 2, s[20:21]
	s_waitcnt vmcnt(14)
	v_pk_add_f32 v[32:33], v[32:33], v[170:171]
	v_pk_add_f32 v[30:31], v[30:31], v[168:169]
	s_waitcnt vmcnt(14)
	v_pk_add_f32 v[40:41], v[40:41], v[174:175]
	v_pk_add_f32 v[38:39], v[38:39], v[172:173]
	global_store_dwordx4 v[148:149], v[30:33], off
	global_store_dwordx4 v[148:149], v[38:41], off offset:64
	s_cbranch_vccnz .LBB0_53
	v_readlane_b32 s20, v253, 54
	v_readlane_b32 s21, v253, 55
	v_cvt_pk_bf16_f32 v144, v30, v31
	v_cvt_pk_bf16_f32 v145, v32, v33
	v_lshl_add_u64 v[138:139], v[138:139], 1, s[20:21]
	global_store_dwordx2 v[138:139], v[144:145], off
	v_cvt_pk_bf16_f32 v144, v38, v39
	v_cvt_pk_bf16_f32 v145, v40, v41
	global_store_dwordx2 v[138:139], v[144:145], off offset:32
.LBB0_53:
	v_readlane_b32 s20, v253, 50
	v_lshl_add_u64 v[136:137], v[136:137], 0, s[18:19]
	v_readlane_b32 s21, v253, 51
	s_and_b64 vcc, exec, s[0:1]
	s_nop 0
	v_lshl_add_u64 v[138:139], v[136:137], 2, s[20:21]
	s_waitcnt vmcnt(14)
	v_pk_add_f32 v[44:45], v[44:45], v[178:179]
	v_pk_add_f32 v[42:43], v[42:43], v[176:177]
	s_waitcnt vmcnt(14)
	v_pk_add_f32 v[48:49], v[48:49], v[182:183]
	v_pk_add_f32 v[46:47], v[46:47], v[180:181]
	global_store_dwordx4 v[138:139], v[42:45], off
	global_store_dwordx4 v[138:139], v[46:49], off offset:64
	s_cbranch_vccnz .LBB0_55
	v_readlane_b32 s20, v253, 54
	v_readlane_b32 s21, v253, 55
	v_cvt_pk_bf16_f32 v138, v42, v43
	v_cvt_pk_bf16_f32 v139, v44, v45
	v_lshl_add_u64 v[136:137], v[136:137], 1, s[20:21]
	global_store_dwordx2 v[136:137], v[138:139], off
	v_cvt_pk_bf16_f32 v138, v46, v47
	v_cvt_pk_bf16_f32 v139, v48, v49
	global_store_dwordx2 v[136:137], v[138:139], off offset:32
; DI void st_bf16x4(bf16_t* p, f32x4 v) { u32x2 o; o.x = pk2e(v[0], v[1]); o.y = pk2e(v[2], v[3]); *(u32x2*)p = o; }
;   DI float operator()(int row, int colbase, int fq, f32x4 v0, f32x4 v1) const { one(row, colbase + 4 * fq, v0); one(row, colbase + 16 + 4 * fq, v1); return 0.f; }
;   DI float operator()(int row, int colbase, int fq, f32x4 v0, f32x4 v1) const { one(row, colbase + 4 * fq, v0); one(row, colbase + 16 + 4 * fq, v1); return 0.f; }
;   DI float operator()(int row, int colbase, int fq, f32x4 v0, f32x4 v1) const { one(row, colbase + 4 * fq, v0); one(row, colbase + 16 + 4 * fq, v1); return 0.f; }
;   DI float operator()(int row, int colbase, int fq, f32x4 v0, f32x4 v1) const { one(row, colbase + 4 * fq, v0); one(row, colbase + 16 + 4 * fq, v1); return 0.f; }
;     ...
; #pragma unroll
;     for (int ai = 0; ai < 2; ++ai)
; #pragma unroll
;       for (int m = 0; m < 4; ++m) {
;         const int row = brow + ai * HALF + wr * 64 + m * 16 + fr_e;
;         const float rsc = epi.rowscale(row);
;         float ssq = 0.f;
; #pragma unroll
;         for (int bj = 0; bj < 2; ++bj)
;           ssq += epi(row, bcol + bj * HALF + wc * 32, fq_e, acc[ai][bj][m][0] * rsc, acc[ai][bj][m][1] * rsc);
;         rowss[ai][m] = ssq;
;         __builtin_amdgcn_sched_barrier(0);
;       }
;   DI float operator()(int row, int colbase, int fq, f32x4 v0, f32x4 v1) const {
;     const size_t o = (size_t)row * D_ + colbase + 4 * fq;
;     const f32x4 a = *(const f32x4*)(src + o) + v0, b = *(const f32x4*)(src + o + 16) + v1;
;     *(f32x4*)(dst + o) = a; *(f32x4*)(dst + o + 16) = b;
;     if (xb) { st_bf16x4(xb + o, a); st_bf16x4(xb + o + 16, b); }
;     return ((a[0] * a[0] + a[1] * a[1]) + (a[2] * a[2] + a[3] * a[3])) + ((b[0] * b[0] + b[1] * b[1]) + (b[2] * b[2] + b[3] * b[3]));
.LBB0_55:
	v_or_b32_e32 v136, 32, v134
	v_ashrrev_i32_e32 v137, 31, v136
	v_lshlrev_b64 v[136:137], 11, v[136:137]
	v_or_b32_e32 v136, v136, v143
	v_readlane_b32 s20, v253, 50
	v_lshl_add_u64 v[138:139], v[136:137], 0, s[16:17]
	v_readlane_b32 s21, v253, 51
	s_and_b64 vcc, exec, s[0:1]
	s_nop 0
	v_lshl_add_u64 v[148:149], v[138:139], 2, s[20:21]
	s_waitcnt vmcnt(14)
	v_pk_add_f32 v[60:61], v[60:61], v[186:187]
	v_pk_add_f32 v[58:59], v[58:59], v[184:185]
	s_waitcnt vmcnt(14)
	v_pk_add_f32 v[64:65], v[64:65], v[190:191]
	v_pk_add_f32 v[62:63], v[62:63], v[188:189]
	global_store_dwordx4 v[148:149], v[58:61], off
	global_store_dwordx4 v[148:149], v[62:65], off offset:64
	s_cbranch_vccnz .LBB0_57
	v_readlane_b32 s20, v253, 54
	v_readlane_b32 s21, v253, 55
	v_cvt_pk_bf16_f32 v144, v58, v59
	v_cvt_pk_bf16_f32 v145, v60, v61
	v_lshl_add_u64 v[138:139], v[138:139], 1, s[20:21]
	global_store_dwordx2 v[138:139], v[144:145], off
	v_cvt_pk_bf16_f32 v144, v62, v63
	v_cvt_pk_bf16_f32 v145, v64, v65
	global_store_dwordx2 v[138:139], v[144:145], off offset:32
.LBB0_57:
	v_readlane_b32 s20, v253, 50
	v_lshl_add_u64 v[136:137], v[136:137], 0, s[18:19]
	v_readlane_b32 s21, v253, 51
	s_and_b64 vcc, exec, s[0:1]
	s_nop 0
	v_lshl_add_u64 v[138:139], v[136:137], 2, s[20:21]
	s_waitcnt vmcnt(14)
	v_pk_add_f32 v[76:77], v[76:77], v[202:203]
	v_pk_add_f32 v[74:75], v[74:75], v[200:201]
	s_waitcnt vmcnt(14)
	v_pk_add_f32 v[80:81], v[80:81], v[206:207]
	v_pk_add_f32 v[78:79], v[78:79], v[204:205]
	global_store_dwordx4 v[138:139], v[74:77], off
	global_store_dwordx4 v[138:139], v[78:81], off offset:64
	s_cbranch_vccnz .LBB0_59
	v_readlane_b32 s20, v253, 54
	v_readlane_b32 s21, v253, 55
	v_cvt_pk_bf16_f32 v138, v74, v75
	v_cvt_pk_bf16_f32 v139, v76, v77
	v_lshl_add_u64 v[136:137], v[136:137], 1, s[20:21]
	global_store_dwordx2 v[136:137], v[138:139], off
	v_cvt_pk_bf16_f32 v138, v78, v79
	v_cvt_pk_bf16_f32 v139, v80, v81
	global_store_dwordx2 v[136:137], v[138:139], off offset:32
.LBB0_59:
	v_or_b32_e32 v136, 48, v134
	v_ashrrev_i32_e32 v137, 31, v136
	v_lshlrev_b64 v[136:137], 11, v[136:137]
	v_or_b32_e32 v136, v136, v143
	v_readlane_b32 s20, v253, 50
	v_lshl_add_u64 v[138:139], v[136:137], 0, s[16:17]
	v_readlane_b32 s21, v253, 51
	s_and_b64 vcc, exec, s[0:1]
	s_nop 0
	v_lshl_add_u64 v[148:149], v[138:139], 2, s[20:21]
	s_waitcnt vmcnt(14)
	v_pk_add_f32 v[84:85], v[84:85], v[210:211]
	v_pk_add_f32 v[82:83], v[82:83], v[208:209]
	s_waitcnt vmcnt(14)
	v_pk_add_f32 v[88:89], v[88:89], v[214:215]
	v_pk_add_f32 v[86:87], v[86:87], v[212:213]
	global_store_dwordx4 v[148:149], v[82:85], off
	global_store_dwordx4 v[148:149], v[86:89], off offset:64
	s_cbranch_vccnz .LBB0_61
	v_readlane_b32 s20, v253, 54
	v_readlane_b32 s21, v253, 55
	v_cvt_pk_bf16_f32 v144, v82, v83
	v_cvt_pk_bf16_f32 v145, v84, v85
	v_lshl_add_u64 v[138:139], v[138:139], 1, s[20:21]
	global_store_dwordx2 v[138:139], v[144:145], off
	v_cvt_pk_bf16_f32 v144, v86, v87
	v_cvt_pk_bf16_f32 v145, v88, v89
	global_store_dwordx2 v[138:139], v[144:145], off offset:32
.LBB0_61:
	v_readlane_b32 s20, v253, 50
	v_lshl_add_u64 v[136:137], v[136:137], 0, s[18:19]
	v_readlane_b32 s21, v253, 51
	s_and_b64 vcc, exec, s[0:1]
	s_nop 0
	v_lshl_add_u64 v[138:139], v[136:137], 2, s[20:21]
	s_waitcnt vmcnt(14)
	v_pk_add_f32 v[100:101], v[100:101], v[218:219]
	v_pk_add_f32 v[98:99], v[98:99], v[216:217]
	s_waitcnt vmcnt(14)
	v_pk_add_f32 v[104:105], v[104:105], v[222:223]
	v_pk_add_f32 v[102:103], v[102:103], v[220:221]
	s_mov_b64 s[100:101], 0xa0000
	v_lshl_add_u64 v[224:225], v[224:225], 0, s[100:101]
	s_mov_b64 s[100:101], 0x20000
	global_load_dwordx4 v[152:155], v[224:225], off
	global_load_dwordx4 v[156:159], v[224:225], off offset:64
	global_load_dwordx4 v[160:163], v[224:225], off offset:512
	global_load_dwordx4 v[164:167], v[224:225], off offset:576
	v_lshl_add_u64 v[224:225], v[224:225], 0, s[100:101]
	global_load_dwordx4 v[168:171], v[224:225], off
	global_load_dwordx4 v[172:175], v[224:225], off offset:64
	global_load_dwordx4 v[176:179], v[224:225], off offset:512
	global_load_dwordx4 v[180:183], v[224:225], off offset:576
	v_lshl_add_u64 v[224:225], v[224:225], 0, s[100:101]
	global_load_dwordx4 v[184:187], v[224:225], off
	global_load_dwordx4 v[188:191], v[224:225], off offset:64
	global_load_dwordx4 v[200:203], v[224:225], off offset:512
	global_load_dwordx4 v[204:207], v[224:225], off offset:576
	v_lshl_add_u64 v[224:225], v[224:225], 0, s[100:101]
	global_load_dwordx4 v[208:211], v[224:225], off
	global_load_dwordx4 v[212:215], v[224:225], off offset:64
	global_load_dwordx4 v[216:219], v[224:225], off offset:512
	global_load_dwordx4 v[220:223], v[224:225], off offset:576
	global_store_dwordx4 v[138:139], v[98:101], off
	global_store_dwordx4 v[138:139], v[102:105], off offset:64
	s_cbranch_vccnz .LBB0_63
	v_readlane_b32 s20, v253, 54
	v_readlane_b32 s21, v253, 55
	v_cvt_pk_bf16_f32 v138, v98, v99
	v_cvt_pk_bf16_f32 v139, v100, v101
	v_lshl_add_u64 v[136:137], v[136:137], 1, s[20:21]
	global_store_dwordx2 v[136:137], v[138:139], off
	v_cvt_pk_bf16_f32 v138, v102, v103
	v_cvt_pk_bf16_f32 v139, v104, v105
	global_store_dwordx2 v[136:137], v[138:139], off offset:32
; DI void st_bf16x4(bf16_t* p, f32x4 v) { u32x2 o; o.x = pk2e(v[0], v[1]); o.y = pk2e(v[2], v[3]); *(u32x2*)p = o; }
;   DI float operator()(int row, int colbase, int fq, f32x4 v0, f32x4 v1) const { one(row, colbase + 4 * fq, v0); one(row, colbase + 16 + 4 * fq, v1); return 0.f; }
;   DI float operator()(int row, int colbase, int fq, f32x4 v0, f32x4 v1) const { one(row, colbase + 4 * fq, v0); one(row, colbase + 16 + 4 * fq, v1); return 0.f; }
;   DI float operator()(int row, int colbase, int fq, f32x4 v0, f32x4 v1) const { one(row, colbase + 4 * fq, v0); one(row, colbase + 16 + 4 * fq, v1); return 0.f; }
;   DI float operator()(int row, int colbase, int fq, f32x4 v0, f32x4 v1) const { one(row, colbase + 4 * fq, v0); one(row, colbase + 16 + 4 * fq, v1); return 0.f; }
;     ...
; #pragma unroll
;     for (int ai = 0; ai < 2; ++ai)
; #pragma unroll
;       for (int m = 0; m < 4; ++m) {
;         const int row = brow + ai * HALF + wr * 64 + m * 16 + fr_e;
;         const float rsc = epi.rowscale(row);
;         float ssq = 0.f;
; #pragma unroll
;         for (int bj = 0; bj < 2; ++bj)
;           ssq += epi(row, bcol + bj * HALF + wc * 32, fq_e, acc[ai][bj][m][0] * rsc, acc[ai][bj][m][1] * rsc);
;         rowss[ai][m] = ssq;
;         __builtin_amdgcn_sched_barrier(0);
;       }
;   DI float operator()(int row, int colbase, int fq, f32x4 v0, f32x4 v1) const {
;     const size_t o = (size_t)row * D_ + colbase + 4 * fq;
;     const f32x4 a = *(const f32x4*)(src + o) + v0, b = *(const f32x4*)(src + o + 16) + v1;
;     *(f32x4*)(dst + o) = a; *(f32x4*)(dst + o + 16) = b;
;     if (xb) { st_bf16x4(xb + o, a); st_bf16x4(xb + o + 16, b); }
;     return ((a[0] * a[0] + a[1] * a[1]) + (a[2] * a[2] + a[3] * a[3])) + ((b[0] * b[0] + b[1] * b[1]) + (b[2] * b[2] + b[3] * b[3]));
.LBB0_63:
	v_add_u32_e32 v136, 0x80, v134
	v_ashrrev_i32_e32 v137, 31, v136
	v_lshlrev_b64 v[136:137], 11, v[136:137]
	v_or_b32_e32 v136, v136, v143
	v_readlane_b32 s20, v253, 50
	v_lshl_add_u64 v[138:139], v[136:137], 0, s[16:17]
	v_readlane_b32 s21, v253, 51
	s_and_b64 vcc, exec, s[0:1]
	s_nop 0
	v_lshl_add_u64 v[148:149], v[138:139], 2, s[20:21]
	s_waitcnt vmcnt(14)
	v_pk_add_f32 v[116:117], v[116:117], v[154:155]
	v_pk_add_f32 v[114:115], v[114:115], v[152:153]
	s_waitcnt vmcnt(14)
	v_pk_add_f32 v[120:121], v[120:121], v[158:159]
	v_pk_add_f32 v[118:119], v[118:119], v[156:157]
	global_store_dwordx4 v[148:149], v[114:117], off
	global_store_dwordx4 v[148:149], v[118:121], off offset:64
	s_cbranch_vccnz .LBB0_65
	v_readlane_b32 s20, v253, 54
	v_readlane_b32 s21, v253, 55
	v_cvt_pk_bf16_f32 v144, v114, v115
	v_cvt_pk_bf16_f32 v145, v116, v117
	v_lshl_add_u64 v[138:139], v[138:139], 1, s[20:21]
	global_store_dwordx2 v[138:139], v[144:145], off
	v_cvt_pk_bf16_f32 v144, v118, v119
	v_cvt_pk_bf16_f32 v145, v120, v121
	global_store_dwordx2 v[138:139], v[144:145], off offset:32
.LBB0_65:
	v_readlane_b32 s20, v253, 50
	v_lshl_add_u64 v[136:137], v[136:137], 0, s[18:19]
	v_readlane_b32 s21, v253, 51
	s_and_b64 vcc, exec, s[0:1]
	s_nop 0
	v_lshl_add_u64 v[138:139], v[136:137], 2, s[20:21]
	s_waitcnt vmcnt(14)
	v_pk_add_f32 v[128:129], v[128:129], v[162:163]
	v_pk_add_f32 v[126:127], v[126:127], v[160:161]
	s_waitcnt vmcnt(14)
	v_pk_add_f32 v[124:125], v[124:125], v[166:167]
	v_pk_add_f32 v[122:123], v[122:123], v[164:165]
	global_store_dwordx4 v[138:139], v[126:129], off
	global_store_dwordx4 v[138:139], v[122:125], off offset:64
	s_cbranch_vccnz .LBB0_67
	v_readlane_b32 s20, v253, 54
	v_readlane_b32 s21, v253, 55
	v_cvt_pk_bf16_f32 v138, v126, v127
	v_cvt_pk_bf16_f32 v139, v128, v129
	v_lshl_add_u64 v[136:137], v[136:137], 1, s[20:21]
	global_store_dwordx2 v[136:137], v[138:139], off
	v_cvt_pk_bf16_f32 v138, v122, v123
	v_cvt_pk_bf16_f32 v139, v124, v125
	global_store_dwordx2 v[136:137], v[138:139], off offset:32
.LBB0_67:
	v_add_u32_e32 v136, 0x90, v134
	v_ashrrev_i32_e32 v137, 31, v136
	v_lshlrev_b64 v[136:137], 11, v[136:137]
	v_or_b32_e32 v136, v136, v143
	v_readlane_b32 s20, v253, 50
	v_lshl_add_u64 v[138:139], v[136:137], 0, s[16:17]
	v_readlane_b32 s21, v253, 51
	s_and_b64 vcc, exec, s[0:1]
	s_nop 0
	v_lshl_add_u64 v[148:149], v[138:139], 2, s[20:21]
	s_waitcnt vmcnt(14)
	v_pk_add_f32 v[112:113], v[112:113], v[170:171]
	v_pk_add_f32 v[110:111], v[110:111], v[168:169]
	s_waitcnt vmcnt(14)
	v_pk_add_f32 v[108:109], v[108:109], v[174:175]
	v_pk_add_f32 v[106:107], v[106:107], v[172:173]
	global_store_dwordx4 v[148:149], v[110:113], off
	global_store_dwordx4 v[148:149], v[106:109], off offset:64
	s_cbranch_vccnz .LBB0_69
	v_readlane_b32 s20, v253, 54
	v_readlane_b32 s21, v253, 55
	v_cvt_pk_bf16_f32 v144, v110, v111
	v_cvt_pk_bf16_f32 v145, v112, v113
	v_lshl_add_u64 v[138:139], v[138:139], 1, s[20:21]
	global_store_dwordx2 v[138:139], v[144:145], off
	v_cvt_pk_bf16_f32 v144, v106, v107
	v_cvt_pk_bf16_f32 v145, v108, v109
	global_store_dwordx2 v[138:139], v[144:145], off offset:32
.LBB0_69:
	v_readlane_b32 s20, v253, 50
	v_lshl_add_u64 v[136:137], v[136:137], 0, s[18:19]
	v_readlane_b32 s21, v253, 51
	s_and_b64 vcc, exec, s[0:1]
	s_nop 0
	v_lshl_add_u64 v[138:139], v[136:137], 2, s[20:21]
	s_waitcnt vmcnt(14)
	v_pk_add_f32 v[96:97], v[96:97], v[178:179]
	v_pk_add_f32 v[94:95], v[94:95], v[176:177]
	s_waitcnt vmcnt(14)
	v_pk_add_f32 v[92:93], v[92:93], v[182:183]
	v_pk_add_f32 v[90:91], v[90:91], v[180:181]
	global_store_dwordx4 v[138:139], v[94:97], off
	global_store_dwordx4 v[138:139], v[90:93], off offset:64
	s_cbranch_vccnz .LBB0_71
	v_readlane_b32 s20, v253, 54
	v_readlane_b32 s21, v253, 55
	v_cvt_pk_bf16_f32 v138, v94, v95
	v_cvt_pk_bf16_f32 v139, v96, v97
	v_lshl_add_u64 v[136:137], v[136:137], 1, s[20:21]
	global_store_dwordx2 v[136:137], v[138:139], off
	v_cvt_pk_bf16_f32 v138, v90, v91
	v_cvt_pk_bf16_f32 v139, v92, v93
	global_store_dwordx2 v[136:137], v[138:139], off offset:32
; DI void st_bf16x4(bf16_t* p, f32x4 v) { u32x2 o; o.x = pk2e(v[0], v[1]); o.y = pk2e(v[2], v[3]); *(u32x2*)p = o; }
;   DI float operator()(int row, int colbase, int fq, f32x4 v0, f32x4 v1) const { one(row, colbase + 4 * fq, v0); one(row, colbase + 16 + 4 * fq, v1); return 0.f; }
;   DI float operator()(int row, int colbase, int fq, f32x4 v0, f32x4 v1) const { one(row, colbase + 4 * fq, v0); one(row, colbase + 16 + 4 * fq, v1); return 0.f; }
;   DI float operator()(int row, int colbase, int fq, f32x4 v0, f32x4 v1) const { one(row, colbase + 4 * fq, v0); one(row, colbase + 16 + 4 * fq, v1); return 0.f; }
;   DI float operator()(int row, int colbase, int fq, f32x4 v0, f32x4 v1) const { one(row, colbase + 4 * fq, v0); one(row, colbase + 16 + 4 * fq, v1); return 0.f; }
;     ...
; #pragma unroll
;     for (int ai = 0; ai < 2; ++ai)
; #pragma unroll
;       for (int m = 0; m < 4; ++m) {
;         const int row = brow + ai * HALF + wr * 64 + m * 16 + fr_e;
;         const float rsc = epi.rowscale(row);
;         float ssq = 0.f;
; #pragma unroll
;         for (int bj = 0; bj < 2; ++bj)
;           ssq += epi(row, bcol + bj * HALF + wc * 32, fq_e, acc[ai][bj][m][0] * rsc, acc[ai][bj][m][1] * rsc);
;         rowss[ai][m] = ssq;
;         __builtin_amdgcn_sched_barrier(0);
;       }
;   DI float operator()(int row, int colbase, int fq, f32x4 v0, f32x4 v1) const {
;     const size_t o = (size_t)row * D_ + colbase + 4 * fq;
;     const f32x4 a = *(const f32x4*)(src + o) + v0, b = *(const f32x4*)(src + o + 16) + v1;
;     *(f32x4*)(dst + o) = a; *(f32x4*)(dst + o + 16) = b;
;     if (xb) { st_bf16x4(xb + o, a); st_bf16x4(xb + o + 16, b); }
;     return ((a[0] * a[0] + a[1] * a[1]) + (a[2] * a[2] + a[3] * a[3])) + ((b[0] * b[0] + b[1] * b[1]) + (b[2] * b[2] + b[3] * b[3]));
.LBB0_71:
	v_add_u32_e32 v136, 0xa0, v134
	v_ashrrev_i32_e32 v137, 31, v136
	v_lshlrev_b64 v[136:137], 11, v[136:137]
	v_or_b32_e32 v136, v136, v143
	v_readlane_b32 s20, v253, 50
	v_lshl_add_u64 v[138:139], v[136:137], 0, s[16:17]
	v_readlane_b32 s21, v253, 51
	s_and_b64 vcc, exec, s[0:1]
	s_nop 0
	v_lshl_add_u64 v[148:149], v[138:139], 2, s[20:21]
	s_waitcnt vmcnt(14)
	v_pk_add_f32 v[72:73], v[72:73], v[186:187]
	v_pk_add_f32 v[70:71], v[70:71], v[184:185]
	s_waitcnt vmcnt(14)
	v_pk_add_f32 v[68:69], v[68:69], v[190:191]
	v_pk_add_f32 v[66:67], v[66:67], v[188:189]
	global_store_dwordx4 v[148:149], v[70:73], off
	global_store_dwordx4 v[148:149], v[66:69], off offset:64
	s_cbranch_vccnz .LBB0_73
	v_readlane_b32 s20, v253, 54
	v_readlane_b32 s21, v253, 55
	v_cvt_pk_bf16_f32 v144, v70, v71
	v_cvt_pk_bf16_f32 v145, v72, v73
	v_lshl_add_u64 v[138:139], v[138:139], 1, s[20:21]
	global_store_dwordx2 v[138:139], v[144:145], off
	v_cvt_pk_bf16_f32 v144, v66, v67
	v_cvt_pk_bf16_f32 v145, v68, v69
	global_store_dwordx2 v[138:139], v[144:145], off offset:32
.LBB0_73:
	v_readlane_b32 s20, v253, 50
	v_lshl_add_u64 v[136:137], v[136:137], 0, s[18:19]
	v_readlane_b32 s21, v253, 51
	s_and_b64 vcc, exec, s[0:1]
	s_nop 0
	v_lshl_add_u64 v[138:139], v[136:137], 2, s[20:21]
	s_waitcnt vmcnt(14)
	v_pk_add_f32 v[56:57], v[56:57], v[202:203]
	v_pk_add_f32 v[54:55], v[54:55], v[200:201]
	s_waitcnt vmcnt(14)
	v_pk_add_f32 v[52:53], v[52:53], v[206:207]
	v_pk_add_f32 v[50:51], v[50:51], v[204:205]
	global_store_dwordx4 v[138:139], v[54:57], off
	global_store_dwordx4 v[138:139], v[50:53], off offset:64
	s_cbranch_vccnz .LBB0_75
	v_readlane_b32 s20, v253, 54
	v_readlane_b32 s21, v253, 55
	v_cvt_pk_bf16_f32 v138, v54, v55
	v_cvt_pk_bf16_f32 v139, v56, v57
	v_lshl_add_u64 v[136:137], v[136:137], 1, s[20:21]
	global_store_dwordx2 v[136:137], v[138:139], off
	v_cvt_pk_bf16_f32 v138, v50, v51
	v_cvt_pk_bf16_f32 v139, v52, v53
	global_store_dwordx2 v[136:137], v[138:139], off offset:32
.LBB0_75:
	v_add_u32_e32 v134, 0xb0, v134
	v_ashrrev_i32_e32 v135, 31, v134
	v_lshlrev_b64 v[134:135], 11, v[134:135]
	v_or_b32_e32 v134, v134, v143
	v_lshl_add_u64 v[136:137], v[134:135], 0, s[16:17]
	v_readlane_b32 s16, v253, 50
	v_readlane_b32 s17, v253, 51
	s_and_b64 vcc, exec, s[0:1]
	s_nop 0
	v_lshl_add_u64 v[138:139], v[136:137], 2, s[16:17]
	s_waitcnt vmcnt(14)
	v_pk_add_f32 v[36:37], v[36:37], v[210:211]
	v_pk_add_f32 v[34:35], v[34:35], v[208:209]
	s_waitcnt vmcnt(14)
	v_pk_add_f32 v[28:29], v[28:29], v[214:215]
	v_pk_add_f32 v[26:27], v[26:27], v[212:213]
	global_store_dwordx4 v[138:139], v[34:37], off
	global_store_dwordx4 v[138:139], v[26:29], off offset:64
	s_cbranch_vccnz .LBB0_77
	v_readlane_b32 s16, v253, 54
	v_readlane_b32 s17, v253, 55
	v_cvt_pk_bf16_f32 v138, v34, v35
	v_cvt_pk_bf16_f32 v139, v36, v37
	v_lshl_add_u64 v[136:137], v[136:137], 1, s[16:17]
	global_store_dwordx2 v[136:137], v[138:139], off
	v_cvt_pk_bf16_f32 v138, v26, v27
	v_cvt_pk_bf16_f32 v139, v28, v29
	global_store_dwordx2 v[136:137], v[138:139], off offset:32
.LBB0_77:
	v_readlane_b32 s16, v253, 50
	v_lshl_add_u64 v[134:135], v[134:135], 0, s[18:19]
	v_readlane_b32 s17, v253, 51
	s_and_b64 vcc, exec, s[0:1]
	s_nop 0
	v_lshl_add_u64 v[144:145], v[134:135], 2, s[16:17]
	s_waitcnt vmcnt(14)
	v_pk_add_f32 v[16:17], v[16:17], v[218:219]
	v_pk_add_f32 v[14:15], v[14:15], v[216:217]
	s_waitcnt vmcnt(14)
	v_pk_add_f32 v[12:13], v[12:13], v[222:223]
	v_pk_add_f32 v[10:11], v[10:11], v[220:221]
	global_store_dwordx4 v[144:145], v[14:17], off
	global_store_dwordx4 v[144:145], v[10:13], off offset:64
	s_cbranch_vccnz .LBB0_79
	v_readlane_b32 s0, v253, 54
	v_readlane_b32 s1, v253, 55
	v_cvt_pk_bf16_f32 v136, v14, v15
	v_cvt_pk_bf16_f32 v137, v16, v17
	v_lshl_add_u64 v[134:135], v[134:135], 1, s[0:1]
	global_store_dwordx2 v[134:135], v[136:137], off
	v_cvt_pk_bf16_f32 v136, v10, v11
	v_cvt_pk_bf16_f32 v137, v12, v13
	global_store_dwordx2 v[134:135], v[136:137], off offset:32

; DI void st_bf16x4(bf16_t* p, f32x4 v) { u32x2 o; o.x = pk2e(v[0], v[1]); o.y = pk2e(v[2], v[3]); *(u32x2*)p = o; }
;   DI float operator()(int row, int colbase, int fq, f32x4 v0, f32x4 v1) const { one(row, colbase + 4 * fq, v0); one(row, colbase + 16 + 4 * fq, v1); return 0.f; }
;   DI float operator()(int row, int colbase, int fq, f32x4 v0, f32x4 v1) const { one(row, colbase + 4 * fq, v0); one(row, colbase + 16 + 4 * fq, v1); return 0.f; }
;   DI float operator()(int row, int colbase, int fq, f32x4 v0, f32x4 v1) const { one(row, colbase + 4 * fq, v0); one(row, colbase + 16 + 4 * fq, v1); return 0.f; }
;   DI float operator()(int row, int colbase, int fq, f32x4 v0, f32x4 v1) const { one(row, colbase + 4 * fq, v0); one(row, colbase + 16 + 4 * fq, v1); return 0.f; }
;     ...
; #pragma unroll
;     for (int ai = 0; ai < 2; ++ai)
; #pragma unroll
;       for (int m = 0; m < 4; ++m) {
;         const int row = brow + ai * HALF + wr * 64 + m * 16 + fr_e;
;         const float rsc = epi.rowscale(row);
;         float ssq = 0.f;
; #pragma unroll
;         for (int bj = 0; bj < 2; ++bj)
;           ssq += epi(row, bcol + bj * HALF + wc * 32, fq_e, acc[ai][bj][m][0] * rsc, acc[ai][bj][m][1] * rsc);
;         rowss[ai][m] = ssq;
;         __builtin_amdgcn_sched_barrier(0);
;       }
;   DI float operator()(int row, int colbase, int fq, f32x4 v0, f32x4 v1) const {
;     const size_t o = (size_t)row * D_ + colbase + 4 * fq;
;     const f32x4 a = *(const f32x4*)(src + o) + v0, b = *(const f32x4*)(src + o + 16) + v1;
;     *(f32x4*)(dst + o) = a; *(f32x4*)(dst + o + 16) = b;
;     if (xb) { st_bf16x4(xb + o, a); st_bf16x4(xb + o + 16, b); }
;     return ((a[0] * a[0] + a[1] * a[1]) + (a[2] * a[2] + a[3] * a[3])) + ((b[0] * b[0] + b[1] * b[1]) + (b[2] * b[2] + b[3] * b[3]));
.LBB0_139:
	v_mov_b32_e32 v134, v199
	s_add_i32 s1, s16, s36
	v_and_b32_e32 v143, 15, v134
	v_bfe_u32 v144, v134, 4, 2
	v_or_b32_e32 v134, s1, v143
	v_ashrrev_i32_e32 v135, 31, v134
	s_or_b32 s18, s0, s37
	v_lshlrev_b32_e32 v145, 2, v144
	v_lshlrev_b64 v[138:139], 11, v[134:135]
	v_or_b32_e32 v138, v138, v145
	s_ashr_i32 s19, s18, 31
	v_lshl_add_u64 v[140:141], v[138:139], 0, s[18:19]
	v_lshlrev_b64 v[150:151], 2, v[140:141]
	v_lshl_add_u64 v[136:137], s[4:5], 0, v[150:151]
	v_mov_b32_e32 v224, v136
	v_mov_b32_e32 v225, v137
	s_mov_b64 s[100:101], 0x20000
	global_load_dwordx4 v[152:155], v[224:225], off
	global_load_dwordx4 v[156:159], v[224:225], off offset:64
	global_load_dwordx4 v[160:163], v[224:225], off offset:512
	global_load_dwordx4 v[164:167], v[224:225], off offset:576
	v_lshl_add_u64 v[224:225], v[224:225], 0, s[100:101]
	global_load_dwordx4 v[168:171], v[224:225], off
	global_load_dwordx4 v[172:175], v[224:225], off offset:64
	global_load_dwordx4 v[176:179], v[224:225], off offset:512
	global_load_dwordx4 v[180:183], v[224:225], off offset:576
	v_lshl_add_u64 v[224:225], v[224:225], 0, s[100:101]
	global_load_dwordx4 v[184:187], v[224:225], off
	global_load_dwordx4 v[188:191], v[224:225], off offset:64
	global_load_dwordx4 v[200:203], v[224:225], off offset:512
	global_load_dwordx4 v[204:207], v[224:225], off offset:576
	v_lshl_add_u64 v[224:225], v[224:225], 0, s[100:101]
	global_load_dwordx4 v[208:211], v[224:225], off
	global_load_dwordx4 v[212:215], v[224:225], off offset:64
	global_load_dwordx4 v[216:219], v[224:225], off offset:512
	global_load_dwordx4 v[220:223], v[224:225], off offset:576
	v_readlane_b32 s0, v253, 50
	v_readlane_b32 s1, v253, 51
	v_cndmask_b32_e64 v135, 0, 1, s[12:13]
	s_andn2_b64 vcc, exec, s[12:13]
	s_waitcnt vmcnt(14)
	v_pk_add_f32 v[4:5], v[4:5], v[154:155]
	v_pk_add_f32 v[2:3], v[2:3], v[152:153]
	s_waitcnt vmcnt(14)
	v_pk_add_f32 v[8:9], v[8:9], v[158:159]
	v_pk_add_f32 v[6:7], v[6:7], v[156:157]
	v_lshl_add_u64 v[146:147], s[0:1], 0, v[150:151]
	v_cmp_ne_u32_e64 s[0:1], 1, v135
	global_store_dwordx4 v[146:147], v[2:5], off
	global_store_dwordx4 v[146:147], v[6:9], off offset:64
	s_cbranch_vccnz .LBB0_141
	v_readlane_b32 s20, v253, 54
	v_readlane_b32 s21, v253, 55
	v_cvt_pk_bf16_f32 v146, v2, v3
	v_cvt_pk_bf16_f32 v147, v4, v5
	v_lshl_add_u64 v[140:141], v[140:141], 1, s[20:21]
	global_store_dwordx2 v[140:141], v[146:147], off
	v_cvt_pk_bf16_f32 v146, v6, v7
	v_cvt_pk_bf16_f32 v147, v8, v9
	global_store_dwordx2 v[140:141], v[146:147], off offset:32
.LBB0_141:
	s_or_b32 s20, s18, 0x80
	s_ashr_i32 s21, s20, 31
	v_readlane_b32 s22, v253, 50
	v_lshl_add_u64 v[138:139], v[138:139], 0, s[20:21]
	v_readlane_b32 s23, v253, 51
	s_and_b64 vcc, exec, s[0:1]
	s_waitcnt vmcnt(14)
	v_pk_add_f32 v[20:21], v[20:21], v[162:163]
	v_pk_add_f32 v[18:19], v[18:19], v[160:161]
	v_lshl_add_u64 v[136:137], v[138:139], 2, s[22:23]
	s_waitcnt vmcnt(14)
	v_pk_add_f32 v[24:25], v[24:25], v[166:167]
	v_pk_add_f32 v[22:23], v[22:23], v[164:165]
	global_store_dwordx4 v[136:137], v[18:21], off
	global_store_dwordx4 v[136:137], v[22:25], off offset:64
	s_cbranch_vccnz .LBB0_143
	v_readlane_b32 s22, v253, 54
	v_readlane_b32 s23, v253, 55
	s_nop 1
	v_lshl_add_u64 v[136:137], v[138:139], 1, s[22:23]
	v_cvt_pk_bf16_f32 v138, v18, v19
	v_cvt_pk_bf16_f32 v139, v20, v21
	global_store_dwordx2 v[136:137], v[138:139], off
	v_cvt_pk_bf16_f32 v138, v22, v23
	v_cvt_pk_bf16_f32 v139, v24, v25
	global_store_dwordx2 v[136:137], v[138:139], off offset:32
.LBB0_143:
	v_or_b32_e32 v136, 16, v134
	v_ashrrev_i32_e32 v137, 31, v136
	v_lshlrev_b64 v[138:139], 11, v[136:137]
	v_or_b32_e32 v138, v138, v145
	v_lshl_add_u64 v[140:141], v[138:139], 0, s[18:19]
	v_lshlrev_b64 v[150:151], 2, v[140:141]
	v_lshl_add_u64 v[136:137], s[4:5], 0, v[150:151]
	v_readlane_b32 s22, v253, 50
	v_readlane_b32 s23, v253, 51
	s_and_b64 vcc, exec, s[0:1]
	s_waitcnt vmcnt(14)
	v_pk_add_f32 v[36:37], v[36:37], v[170:171]
	v_pk_add_f32 v[34:35], v[34:35], v[168:169]
	s_waitcnt vmcnt(14)
	v_pk_add_f32 v[40:41], v[40:41], v[174:175]
	v_pk_add_f32 v[38:39], v[38:39], v[172:173]
	v_lshl_add_u64 v[146:147], s[22:23], 0, v[150:151]
	global_store_dwordx4 v[146:147], v[34:37], off
	global_store_dwordx4 v[146:147], v[38:41], off offset:64
	s_cbranch_vccnz .LBB0_145
	v_readlane_b32 s22, v253, 54
	v_readlane_b32 s23, v253, 55
	v_cvt_pk_bf16_f32 v146, v34, v35
	v_cvt_pk_bf16_f32 v147, v36, v37
	v_lshl_add_u64 v[140:141], v[140:141], 1, s[22:23]
	global_store_dwordx2 v[140:141], v[146:147], off
	v_cvt_pk_bf16_f32 v146, v38, v39
	v_cvt_pk_bf16_f32 v147, v40, v41
	global_store_dwordx2 v[140:141], v[146:147], off offset:32
.LBB0_145:
	v_readlane_b32 s22, v253, 50
	v_lshl_add_u64 v[138:139], v[138:139], 0, s[20:21]
	v_readlane_b32 s23, v253, 51
	s_and_b64 vcc, exec, s[0:1]
	s_waitcnt vmcnt(14)
	v_pk_add_f32 v[44:45], v[44:45], v[178:179]
	v_pk_add_f32 v[42:43], v[42:43], v[176:177]
	v_lshl_add_u64 v[136:137], v[138:139], 2, s[22:23]
	s_waitcnt vmcnt(14)
	v_pk_add_f32 v[48:49], v[48:49], v[182:183]
	v_pk_add_f32 v[46:47], v[46:47], v[180:181]
	global_store_dwordx4 v[136:137], v[42:45], off
	global_store_dwordx4 v[136:137], v[46:49], off offset:64
	s_cbranch_vccnz .LBB0_147
	v_readlane_b32 s22, v253, 54
	v_readlane_b32 s23, v253, 55
	s_nop 1
	v_lshl_add_u64 v[136:137], v[138:139], 1, s[22:23]
	v_cvt_pk_bf16_f32 v138, v42, v43
	v_cvt_pk_bf16_f32 v139, v44, v45
	global_store_dwordx2 v[136:137], v[138:139], off
	v_cvt_pk_bf16_f32 v138, v46, v47
	v_cvt_pk_bf16_f32 v139, v48, v49
	global_store_dwordx2 v[136:137], v[138:139], off offset:32
; DI void st_bf16x4(bf16_t* p, f32x4 v) { u32x2 o; o.x = pk2e(v[0], v[1]); o.y = pk2e(v[2], v[3]); *(u32x2*)p = o; }
;   DI float operator()(int row, int colbase, int fq, f32x4 v0, f32x4 v1) const { one(row, colbase + 4 * fq, v0); one(row, colbase + 16 + 4 * fq, v1); return 0.f; }
;   DI float operator()(int row, int colbase, int fq, f32x4 v0, f32x4 v1) const { one(row, colbase + 4 * fq, v0); one(row, colbase + 16 + 4 * fq, v1); return 0.f; }
;   DI float operator()(int row, int colbase, int fq, f32x4 v0, f32x4 v1) const { one(row, colbase + 4 * fq, v0); one(row, colbase + 16 + 4 * fq, v1); return 0.f; }
;   DI float operator()(int row, int colbase, int fq, f32x4 v0, f32x4 v1) const { one(row, colbase + 4 * fq, v0); one(row, colbase + 16 + 4 * fq, v1); return 0.f; }
;     ...
; #pragma unroll
;     for (int ai = 0; ai < 2; ++ai)
; #pragma unroll
;       for (int m = 0; m < 4; ++m) {
;         const int row = brow + ai * HALF + wr * 64 + m * 16 + fr_e;
;         const float rsc = epi.rowscale(row);
;         float ssq = 0.f;
; #pragma unroll
;         for (int bj = 0; bj < 2; ++bj)
;           ssq += epi(row, bcol + bj * HALF + wc * 32, fq_e, acc[ai][bj][m][0] * rsc, acc[ai][bj][m][1] * rsc);
;         rowss[ai][m] = ssq;
;         __builtin_amdgcn_sched_barrier(0);
;       }
;   DI float operator()(int row, int colbase, int fq, f32x4 v0, f32x4 v1) const {
;     const size_t o = (size_t)row * D_ + colbase + 4 * fq;
;     const f32x4 a = *(const f32x4*)(src + o) + v0, b = *(const f32x4*)(src + o + 16) + v1;
;     *(f32x4*)(dst + o) = a; *(f32x4*)(dst + o + 16) = b;
;     if (xb) { st_bf16x4(xb + o, a); st_bf16x4(xb + o + 16, b); }
;     return ((a[0] * a[0] + a[1] * a[1]) + (a[2] * a[2] + a[3] * a[3])) + ((b[0] * b[0] + b[1] * b[1]) + (b[2] * b[2] + b[3] * b[3]));
.LBB0_147:
	v_or_b32_e32 v136, 32, v134
	v_ashrrev_i32_e32 v137, 31, v136
	v_lshlrev_b64 v[138:139], 11, v[136:137]
	v_or_b32_e32 v138, v138, v145
	v_lshl_add_u64 v[140:141], v[138:139], 0, s[18:19]
	v_lshlrev_b64 v[150:151], 2, v[140:141]
	v_lshl_add_u64 v[136:137], s[4:5], 0, v[150:151]
	v_readlane_b32 s22, v253, 50
	v_readlane_b32 s23, v253, 51
	s_and_b64 vcc, exec, s[0:1]
	s_waitcnt vmcnt(14)
	v_pk_add_f32 v[60:61], v[60:61], v[186:187]
	v_pk_add_f32 v[58:59], v[58:59], v[184:185]
	s_waitcnt vmcnt(14)
	v_pk_add_f32 v[64:65], v[64:65], v[190:191]
	v_pk_add_f32 v[62:63], v[62:63], v[188:189]
	v_lshl_add_u64 v[146:147], s[22:23], 0, v[150:151]
	global_store_dwordx4 v[146:147], v[58:61], off
	global_store_dwordx4 v[146:147], v[62:65], off offset:64
	s_cbranch_vccnz .LBB0_149
	v_readlane_b32 s22, v253, 54
	v_readlane_b32 s23, v253, 55
	v_cvt_pk_bf16_f32 v146, v58, v59
	v_cvt_pk_bf16_f32 v147, v60, v61
	v_lshl_add_u64 v[140:141], v[140:141], 1, s[22:23]
	global_store_dwordx2 v[140:141], v[146:147], off
	v_cvt_pk_bf16_f32 v146, v62, v63
	v_cvt_pk_bf16_f32 v147, v64, v65
	global_store_dwordx2 v[140:141], v[146:147], off offset:32
.LBB0_149:
	v_readlane_b32 s22, v253, 50
	v_lshl_add_u64 v[138:139], v[138:139], 0, s[20:21]
	v_readlane_b32 s23, v253, 51
	s_and_b64 vcc, exec, s[0:1]
	s_waitcnt vmcnt(14)
	v_pk_add_f32 v[76:77], v[76:77], v[202:203]
	v_pk_add_f32 v[74:75], v[74:75], v[200:201]
	v_lshl_add_u64 v[136:137], v[138:139], 2, s[22:23]
	s_waitcnt vmcnt(14)
	v_pk_add_f32 v[80:81], v[80:81], v[206:207]
	v_pk_add_f32 v[78:79], v[78:79], v[204:205]
	global_store_dwordx4 v[136:137], v[74:77], off
	global_store_dwordx4 v[136:137], v[78:81], off offset:64
	s_cbranch_vccnz .LBB0_151
	v_readlane_b32 s22, v253, 54
	v_readlane_b32 s23, v253, 55
	s_nop 1
	v_lshl_add_u64 v[136:137], v[138:139], 1, s[22:23]
	v_cvt_pk_bf16_f32 v138, v74, v75
	v_cvt_pk_bf16_f32 v139, v76, v77
	global_store_dwordx2 v[136:137], v[138:139], off
	v_cvt_pk_bf16_f32 v138, v78, v79
	v_cvt_pk_bf16_f32 v139, v80, v81
	global_store_dwordx2 v[136:137], v[138:139], off offset:32
.LBB0_151:
	v_or_b32_e32 v136, 48, v134
	v_ashrrev_i32_e32 v137, 31, v136
	v_lshlrev_b64 v[138:139], 11, v[136:137]
	v_or_b32_e32 v138, v138, v145
	v_lshl_add_u64 v[140:141], v[138:139], 0, s[18:19]
	v_lshlrev_b64 v[150:151], 2, v[140:141]
	v_lshl_add_u64 v[136:137], s[4:5], 0, v[150:151]
	v_readlane_b32 s22, v253, 50
	v_readlane_b32 s23, v253, 51
	s_and_b64 vcc, exec, s[0:1]
	s_waitcnt vmcnt(14)
	v_pk_add_f32 v[88:89], v[88:89], v[210:211]
	v_pk_add_f32 v[86:87], v[86:87], v[208:209]
	s_waitcnt vmcnt(14)
	v_pk_add_f32 v[96:97], v[96:97], v[214:215]
	v_pk_add_f32 v[94:95], v[94:95], v[212:213]
	v_lshl_add_u64 v[146:147], s[22:23], 0, v[150:151]
	global_store_dwordx4 v[146:147], v[86:89], off
	global_store_dwordx4 v[146:147], v[94:97], off offset:64
	s_cbranch_vccnz .LBB0_153
	v_readlane_b32 s22, v253, 54
	v_readlane_b32 s23, v253, 55
	v_cvt_pk_bf16_f32 v146, v86, v87
	v_cvt_pk_bf16_f32 v147, v88, v89
	v_lshl_add_u64 v[140:141], v[140:141], 1, s[22:23]
	global_store_dwordx2 v[140:141], v[146:147], off
	v_cvt_pk_bf16_f32 v146, v94, v95
	v_cvt_pk_bf16_f32 v147, v96, v97
	global_store_dwordx2 v[140:141], v[146:147], off offset:32
.LBB0_153:
	v_readlane_b32 s22, v253, 50
	v_lshl_add_u64 v[138:139], v[138:139], 0, s[20:21]
	v_readlane_b32 s23, v253, 51
	s_and_b64 vcc, exec, s[0:1]
	s_waitcnt vmcnt(14)
	v_pk_add_f32 v[104:105], v[104:105], v[218:219]
	v_pk_add_f32 v[102:103], v[102:103], v[216:217]
	v_lshl_add_u64 v[136:137], v[138:139], 2, s[22:23]
	s_waitcnt vmcnt(14)
	v_pk_add_f32 v[112:113], v[112:113], v[222:223]
	v_pk_add_f32 v[110:111], v[110:111], v[220:221]
	s_mov_b64 s[100:101], 0xa0000
	v_lshl_add_u64 v[224:225], v[224:225], 0, s[100:101]
	s_mov_b64 s[100:101], 0x20000
	global_load_dwordx4 v[152:155], v[224:225], off
	global_load_dwordx4 v[156:159], v[224:225], off offset:64
	global_load_dwordx4 v[160:163], v[224:225], off offset:512
	global_load_dwordx4 v[164:167], v[224:225], off offset:576
	v_lshl_add_u64 v[224:225], v[224:225], 0, s[100:101]
	global_load_dwordx4 v[168:171], v[224:225], off
	global_load_dwordx4 v[172:175], v[224:225], off offset:64
	global_load_dwordx4 v[176:179], v[224:225], off offset:512
	global_load_dwordx4 v[180:183], v[224:225], off offset:576
	v_lshl_add_u64 v[224:225], v[224:225], 0, s[100:101]
	global_load_dwordx4 v[184:187], v[224:225], off
	global_load_dwordx4 v[188:191], v[224:225], off offset:64
	global_load_dwordx4 v[200:203], v[224:225], off offset:512
	global_load_dwordx4 v[204:207], v[224:225], off offset:576
	v_lshl_add_u64 v[224:225], v[224:225], 0, s[100:101]
	global_load_dwordx4 v[208:211], v[224:225], off
	global_load_dwordx4 v[212:215], v[224:225], off offset:64
	global_load_dwordx4 v[216:219], v[224:225], off offset:512
	global_load_dwordx4 v[220:223], v[224:225], off offset:576
	global_store_dwordx4 v[136:137], v[102:105], off
	global_store_dwordx4 v[136:137], v[110:113], off offset:64
	s_cbranch_vccnz .LBB0_155
	v_readlane_b32 s22, v253, 54
	v_readlane_b32 s23, v253, 55
	s_nop 1
	v_lshl_add_u64 v[136:137], v[138:139], 1, s[22:23]
	v_cvt_pk_bf16_f32 v138, v102, v103
	v_cvt_pk_bf16_f32 v139, v104, v105
	global_store_dwordx2 v[136:137], v[138:139], off
	v_cvt_pk_bf16_f32 v138, v110, v111
	v_cvt_pk_bf16_f32 v139, v112, v113
	global_store_dwordx2 v[136:137], v[138:139], off offset:32
; DI void st_bf16x4(bf16_t* p, f32x4 v) { u32x2 o; o.x = pk2e(v[0], v[1]); o.y = pk2e(v[2], v[3]); *(u32x2*)p = o; }
;   DI float operator()(int row, int colbase, int fq, f32x4 v0, f32x4 v1) const { one(row, colbase + 4 * fq, v0); one(row, colbase + 16 + 4 * fq, v1); return 0.f; }
;   DI float operator()(int row, int colbase, int fq, f32x4 v0, f32x4 v1) const { one(row, colbase + 4 * fq, v0); one(row, colbase + 16 + 4 * fq, v1); return 0.f; }
;   DI float operator()(int row, int colbase, int fq, f32x4 v0, f32x4 v1) const { one(row, colbase + 4 * fq, v0); one(row, colbase + 16 + 4 * fq, v1); return 0.f; }
;   DI float operator()(int row, int colbase, int fq, f32x4 v0, f32x4 v1) const { one(row, colbase + 4 * fq, v0); one(row, colbase + 16 + 4 * fq, v1); return 0.f; }
;     ...
; #pragma unroll
;     for (int ai = 0; ai < 2; ++ai)
; #pragma unroll
;       for (int m = 0; m < 4; ++m) {
;         const int row = brow + ai * HALF + wr * 64 + m * 16 + fr_e;
;         const float rsc = epi.rowscale(row);
;         float ssq = 0.f;
; #pragma unroll
;         for (int bj = 0; bj < 2; ++bj)
;           ssq += epi(row, bcol + bj * HALF + wc * 32, fq_e, acc[ai][bj][m][0] * rsc, acc[ai][bj][m][1] * rsc);
;         rowss[ai][m] = ssq;
;         __builtin_amdgcn_sched_barrier(0);
;       }
;   DI float operator()(int row, int colbase, int fq, f32x4 v0, f32x4 v1) const {
;     const size_t o = (size_t)row * D_ + colbase + 4 * fq;
;     const f32x4 a = *(const f32x4*)(src + o) + v0, b = *(const f32x4*)(src + o + 16) + v1;
;     *(f32x4*)(dst + o) = a; *(f32x4*)(dst + o + 16) = b;
;     if (xb) { st_bf16x4(xb + o, a); st_bf16x4(xb + o + 16, b); }
;     return ((a[0] * a[0] + a[1] * a[1]) + (a[2] * a[2] + a[3] * a[3])) + ((b[0] * b[0] + b[1] * b[1]) + (b[2] * b[2] + b[3] * b[3]));
.LBB0_155:
	v_add_u32_e32 v136, 0x80, v134
	v_ashrrev_i32_e32 v137, 31, v136
	v_lshlrev_b64 v[138:139], 11, v[136:137]
	v_or_b32_e32 v138, v138, v145
	v_lshl_add_u64 v[140:141], v[138:139], 0, s[18:19]
	v_lshlrev_b64 v[150:151], 2, v[140:141]
	v_lshl_add_u64 v[136:137], s[4:5], 0, v[150:151]
	v_readlane_b32 s22, v253, 50
	v_readlane_b32 s23, v253, 51
	s_and_b64 vcc, exec, s[0:1]
	s_waitcnt vmcnt(14)
	v_pk_add_f32 v[116:117], v[116:117], v[154:155]
	v_pk_add_f32 v[114:115], v[114:115], v[152:153]
	s_waitcnt vmcnt(14)
	v_pk_add_f32 v[120:121], v[120:121], v[158:159]
	v_pk_add_f32 v[118:119], v[118:119], v[156:157]
	v_lshl_add_u64 v[146:147], s[22:23], 0, v[150:151]
	global_store_dwordx4 v[146:147], v[114:117], off
	global_store_dwordx4 v[146:147], v[118:121], off offset:64
	s_cbranch_vccnz .LBB0_157
	v_readlane_b32 s22, v253, 54
	v_readlane_b32 s23, v253, 55
	v_cvt_pk_bf16_f32 v146, v114, v115
	v_cvt_pk_bf16_f32 v147, v116, v117
	v_lshl_add_u64 v[140:141], v[140:141], 1, s[22:23]
	global_store_dwordx2 v[140:141], v[146:147], off
	v_cvt_pk_bf16_f32 v146, v118, v119
	v_cvt_pk_bf16_f32 v147, v120, v121
	global_store_dwordx2 v[140:141], v[146:147], off offset:32
.LBB0_157:
	v_readlane_b32 s22, v253, 50
	v_lshl_add_u64 v[138:139], v[138:139], 0, s[20:21]
	v_readlane_b32 s23, v253, 51
	s_and_b64 vcc, exec, s[0:1]
	s_waitcnt vmcnt(14)
	v_pk_add_f32 v[128:129], v[128:129], v[162:163]
	v_pk_add_f32 v[126:127], v[126:127], v[160:161]
	v_lshl_add_u64 v[136:137], v[138:139], 2, s[22:23]
	s_waitcnt vmcnt(14)
	v_pk_add_f32 v[124:125], v[124:125], v[166:167]
	v_pk_add_f32 v[122:123], v[122:123], v[164:165]
	global_store_dwordx4 v[136:137], v[126:129], off
	global_store_dwordx4 v[136:137], v[122:125], off offset:64
	s_cbranch_vccnz .LBB0_159
	v_readlane_b32 s22, v253, 54
	v_readlane_b32 s23, v253, 55
	s_nop 1
	v_lshl_add_u64 v[136:137], v[138:139], 1, s[22:23]
	v_cvt_pk_bf16_f32 v138, v126, v127
	v_cvt_pk_bf16_f32 v139, v128, v129
	global_store_dwordx2 v[136:137], v[138:139], off
	v_cvt_pk_bf16_f32 v138, v122, v123
	v_cvt_pk_bf16_f32 v139, v124, v125
	global_store_dwordx2 v[136:137], v[138:139], off offset:32
.LBB0_159:
	v_add_u32_e32 v136, 0x90, v134
	v_ashrrev_i32_e32 v137, 31, v136
	v_lshlrev_b64 v[138:139], 11, v[136:137]
	v_or_b32_e32 v138, v138, v145
	v_lshl_add_u64 v[140:141], v[138:139], 0, s[18:19]
	v_lshlrev_b64 v[150:151], 2, v[140:141]
	v_lshl_add_u64 v[136:137], s[4:5], 0, v[150:151]
	v_readlane_b32 s22, v253, 50
	v_readlane_b32 s23, v253, 51
	s_and_b64 vcc, exec, s[0:1]
	s_waitcnt vmcnt(14)
	v_pk_add_f32 v[108:109], v[108:109], v[170:171]
	v_pk_add_f32 v[106:107], v[106:107], v[168:169]
	s_waitcnt vmcnt(14)
	v_pk_add_f32 v[100:101], v[100:101], v[174:175]
	v_pk_add_f32 v[98:99], v[98:99], v[172:173]
	v_lshl_add_u64 v[146:147], s[22:23], 0, v[150:151]
	global_store_dwordx4 v[146:147], v[106:109], off
	global_store_dwordx4 v[146:147], v[98:101], off offset:64
	s_cbranch_vccnz .LBB0_161
	v_readlane_b32 s22, v253, 54
	v_readlane_b32 s23, v253, 55
	v_cvt_pk_bf16_f32 v146, v106, v107
	v_cvt_pk_bf16_f32 v147, v108, v109
	v_lshl_add_u64 v[140:141], v[140:141], 1, s[22:23]
	global_store_dwordx2 v[140:141], v[146:147], off
	v_cvt_pk_bf16_f32 v146, v98, v99
	v_cvt_pk_bf16_f32 v147, v100, v101
	global_store_dwordx2 v[140:141], v[146:147], off offset:32
.LBB0_161:
	v_readlane_b32 s22, v253, 50
	v_lshl_add_u64 v[138:139], v[138:139], 0, s[20:21]
	v_readlane_b32 s23, v253, 51
	s_and_b64 vcc, exec, s[0:1]
	s_waitcnt vmcnt(14)
	v_pk_add_f32 v[92:93], v[92:93], v[178:179]
	v_pk_add_f32 v[90:91], v[90:91], v[176:177]
	v_lshl_add_u64 v[136:137], v[138:139], 2, s[22:23]
	s_waitcnt vmcnt(14)
	v_pk_add_f32 v[84:85], v[84:85], v[182:183]
	v_pk_add_f32 v[82:83], v[82:83], v[180:181]
	global_store_dwordx4 v[136:137], v[90:93], off
	global_store_dwordx4 v[136:137], v[82:85], off offset:64
	s_cbranch_vccnz .LBB0_163
	v_readlane_b32 s22, v253, 54
	v_readlane_b32 s23, v253, 55
	s_nop 1
	v_lshl_add_u64 v[136:137], v[138:139], 1, s[22:23]
	v_cvt_pk_bf16_f32 v138, v90, v91
	v_cvt_pk_bf16_f32 v139, v92, v93
	global_store_dwordx2 v[136:137], v[138:139], off
	v_cvt_pk_bf16_f32 v138, v82, v83
	v_cvt_pk_bf16_f32 v139, v84, v85
	global_store_dwordx2 v[136:137], v[138:139], off offset:32
; DI void st_bf16x4(bf16_t* p, f32x4 v) { u32x2 o; o.x = pk2e(v[0], v[1]); o.y = pk2e(v[2], v[3]); *(u32x2*)p = o; }
;   DI float operator()(int row, int colbase, int fq, f32x4 v0, f32x4 v1) const { one(row, colbase + 4 * fq, v0); one(row, colbase + 16 + 4 * fq, v1); return 0.f; }
;   DI float operator()(int row, int colbase, int fq, f32x4 v0, f32x4 v1) const { one(row, colbase + 4 * fq, v0); one(row, colbase + 16 + 4 * fq, v1); return 0.f; }
;   DI float operator()(int row, int colbase, int fq, f32x4 v0, f32x4 v1) const { one(row, colbase + 4 * fq, v0); one(row, colbase + 16 + 4 * fq, v1); return 0.f; }
;   DI float operator()(int row, int colbase, int fq, f32x4 v0, f32x4 v1) const { one(row, colbase + 4 * fq, v0); one(row, colbase + 16 + 4 * fq, v1); return 0.f; }
;     ...
; #pragma unroll
;     for (int ai = 0; ai < 2; ++ai)
; #pragma unroll
;       for (int m = 0; m < 4; ++m) {
;         const int row = brow + ai * HALF + wr * 64 + m * 16 + fr_e;
;         const float rsc = epi.rowscale(row);
;         float ssq = 0.f;
; #pragma unroll
;         for (int bj = 0; bj < 2; ++bj)
;           ssq += epi(row, bcol + bj * HALF + wc * 32, fq_e, acc[ai][bj][m][0] * rsc, acc[ai][bj][m][1] * rsc);
;         rowss[ai][m] = ssq;
;         __builtin_amdgcn_sched_barrier(0);
;       }
;   DI float operator()(int row, int colbase, int fq, f32x4 v0, f32x4 v1) const {
;     const size_t o = (size_t)row * D_ + colbase + 4 * fq;
;     const f32x4 a = *(const f32x4*)(src + o) + v0, b = *(const f32x4*)(src + o + 16) + v1;
;     *(f32x4*)(dst + o) = a; *(f32x4*)(dst + o + 16) = b;
;     if (xb) { st_bf16x4(xb + o, a); st_bf16x4(xb + o + 16, b); }
;     return ((a[0] * a[0] + a[1] * a[1]) + (a[2] * a[2] + a[3] * a[3])) + ((b[0] * b[0] + b[1] * b[1]) + (b[2] * b[2] + b[3] * b[3]));
.LBB0_163:
	v_add_u32_e32 v136, 0xa0, v134
	v_ashrrev_i32_e32 v137, 31, v136
	v_lshlrev_b64 v[138:139], 11, v[136:137]
	v_or_b32_e32 v138, v138, v145
	v_lshl_add_u64 v[140:141], v[138:139], 0, s[18:19]
	v_lshlrev_b64 v[150:151], 2, v[140:141]
	v_lshl_add_u64 v[136:137], s[4:5], 0, v[150:151]
	v_readlane_b32 s22, v253, 50
	v_readlane_b32 s23, v253, 51
	s_and_b64 vcc, exec, s[0:1]
	s_waitcnt vmcnt(14)
	v_pk_add_f32 v[72:73], v[72:73], v[186:187]
	v_pk_add_f32 v[70:71], v[70:71], v[184:185]
	s_waitcnt vmcnt(14)
	v_pk_add_f32 v[68:69], v[68:69], v[190:191]
	v_pk_add_f32 v[66:67], v[66:67], v[188:189]
	v_lshl_add_u64 v[146:147], s[22:23], 0, v[150:151]
	global_store_dwordx4 v[146:147], v[70:73], off
	global_store_dwordx4 v[146:147], v[66:69], off offset:64
	s_cbranch_vccnz .LBB0_165
	v_readlane_b32 s22, v253, 54
	v_readlane_b32 s23, v253, 55
	v_cvt_pk_bf16_f32 v146, v70, v71
	v_cvt_pk_bf16_f32 v147, v72, v73
	v_lshl_add_u64 v[140:141], v[140:141], 1, s[22:23]
	global_store_dwordx2 v[140:141], v[146:147], off
	v_cvt_pk_bf16_f32 v146, v66, v67
	v_cvt_pk_bf16_f32 v147, v68, v69
	global_store_dwordx2 v[140:141], v[146:147], off offset:32
.LBB0_165:
	v_readlane_b32 s22, v253, 50
	v_lshl_add_u64 v[138:139], v[138:139], 0, s[20:21]
	v_readlane_b32 s23, v253, 51
	s_and_b64 vcc, exec, s[0:1]
	s_waitcnt vmcnt(14)
	v_pk_add_f32 v[56:57], v[56:57], v[202:203]
	v_pk_add_f32 v[54:55], v[54:55], v[200:201]
	v_lshl_add_u64 v[136:137], v[138:139], 2, s[22:23]
	s_waitcnt vmcnt(14)
	v_pk_add_f32 v[52:53], v[52:53], v[206:207]
	v_pk_add_f32 v[50:51], v[50:51], v[204:205]
	global_store_dwordx4 v[136:137], v[54:57], off
	global_store_dwordx4 v[136:137], v[50:53], off offset:64
	s_cbranch_vccnz .LBB0_167
	v_readlane_b32 s22, v253, 54
	v_readlane_b32 s23, v253, 55
	s_nop 1
	v_lshl_add_u64 v[136:137], v[138:139], 1, s[22:23]
	v_cvt_pk_bf16_f32 v138, v54, v55
	v_cvt_pk_bf16_f32 v139, v56, v57
	global_store_dwordx2 v[136:137], v[138:139], off
	v_cvt_pk_bf16_f32 v138, v50, v51
	v_cvt_pk_bf16_f32 v139, v52, v53
	global_store_dwordx2 v[136:137], v[138:139], off offset:32
.LBB0_167:
	v_add_u32_e32 v134, 0xb0, v134
	v_ashrrev_i32_e32 v135, 31, v134
	v_lshlrev_b64 v[136:137], 11, v[134:135]
	v_or_b32_e32 v136, v136, v145
	v_lshl_add_u64 v[138:139], v[136:137], 0, s[18:19]
	v_lshlrev_b64 v[140:141], 2, v[138:139]
	v_lshl_add_u64 v[134:135], s[4:5], 0, v[140:141]
	v_readlane_b32 s18, v253, 50
	v_readlane_b32 s19, v253, 51
	s_and_b64 vcc, exec, s[0:1]
	s_waitcnt vmcnt(14)
	v_pk_add_f32 v[32:33], v[32:33], v[210:211]
	v_pk_add_f32 v[30:31], v[30:31], v[208:209]
	v_lshl_add_u64 v[140:141], s[18:19], 0, v[140:141]
	s_waitcnt vmcnt(14)
	v_pk_add_f32 v[28:29], v[28:29], v[214:215]
	v_pk_add_f32 v[26:27], v[26:27], v[212:213]
	global_store_dwordx4 v[140:141], v[30:33], off
	global_store_dwordx4 v[140:141], v[26:29], off offset:64
	s_cbranch_vccnz .LBB0_169
	v_readlane_b32 s18, v253, 54
	v_readlane_b32 s19, v253, 55
	v_cvt_pk_bf16_f32 v140, v30, v31
	v_cvt_pk_bf16_f32 v141, v32, v33
	v_lshl_add_u64 v[138:139], v[138:139], 1, s[18:19]
	global_store_dwordx2 v[138:139], v[140:141], off
	v_cvt_pk_bf16_f32 v140, v26, v27
	v_cvt_pk_bf16_f32 v141, v28, v29
	global_store_dwordx2 v[138:139], v[140:141], off offset:32
.LBB0_169:
	v_readlane_b32 s18, v253, 50
	v_lshl_add_u64 v[136:137], v[136:137], 0, s[20:21]
	v_readlane_b32 s19, v253, 51
	s_and_b64 vcc, exec, s[0:1]
	s_waitcnt vmcnt(14)
	v_pk_add_f32 v[16:17], v[16:17], v[218:219]
	v_pk_add_f32 v[14:15], v[14:15], v[216:217]
	v_lshl_add_u64 v[134:135], v[136:137], 2, s[18:19]
	s_waitcnt vmcnt(14)
	v_pk_add_f32 v[12:13], v[12:13], v[222:223]
	v_pk_add_f32 v[10:11], v[10:11], v[220:221]
	global_store_dwordx4 v[134:135], v[14:17], off
	global_store_dwordx4 v[134:135], v[10:13], off offset:64
	s_cbranch_vccnz .LBB0_171
	v_readlane_b32 s0, v253, 54
	v_readlane_b32 s1, v253, 55
	s_nop 1
	v_lshl_add_u64 v[134:135], v[136:137], 1, s[0:1]
	v_cvt_pk_bf16_f32 v136, v14, v15
	v_cvt_pk_bf16_f32 v137, v16, v17
	global_store_dwordx2 v[134:135], v[136:137], off
	v_cvt_pk_bf16_f32 v136, v10, v11
	v_cvt_pk_bf16_f32 v137, v12, v13
	global_store_dwordx2 v[134:135], v[136:137], off offset:32

; DI void st_bf16x4(bf16_t* p, f32x4 v) { u32x2 o; o.x = pk2e(v[0], v[1]); o.y = pk2e(v[2], v[3]); *(u32x2*)p = o; }
;   DI float operator()(int row, int colbase, int fq, f32x4 v0, f32x4 v1) const { one(row, colbase + 4 * fq, v0); one(row, colbase + 16 + 4 * fq, v1); return 0.f; }
;   DI float operator()(int row, int colbase, int fq, f32x4 v0, f32x4 v1) const { one(row, colbase + 4 * fq, v0); one(row, colbase + 16 + 4 * fq, v1); return 0.f; }
;   DI float operator()(int row, int colbase, int fq, f32x4 v0, f32x4 v1) const { one(row, colbase + 4 * fq, v0); one(row, colbase + 16 + 4 * fq, v1); return 0.f; }
;   DI float operator()(int row, int colbase, int fq, f32x4 v0, f32x4 v1) const { one(row, colbase + 4 * fq, v0); one(row, colbase + 16 + 4 * fq, v1); return 0.f; }
;     ...
; #pragma unroll
;     for (int ai = 0; ai < 2; ++ai)
; #pragma unroll
;       for (int m = 0; m < 4; ++m) {
;         const int row = brow + ai * HALF + wr * 64 + m * 16 + fr_e;
;         const float rsc = epi.rowscale(row);
;         float ssq = 0.f;
; #pragma unroll
;         for (int bj = 0; bj < 2; ++bj)
;           ssq += epi(row, bcol + bj * HALF + wc * 32, fq_e, acc[ai][bj][m][0] * rsc, acc[ai][bj][m][1] * rsc);
;         rowss[ai][m] = ssq;
;         __builtin_amdgcn_sched_barrier(0);
;       }
;   DI float operator()(int row, int colbase, int fq, f32x4 v0, f32x4 v1) const {
;     const size_t o = (size_t)row * D_ + colbase + 4 * fq;
;     const f32x4 a = *(const f32x4*)(src + o) + v0, b = *(const f32x4*)(src + o + 16) + v1;
;     *(f32x4*)(dst + o) = a; *(f32x4*)(dst + o + 16) = b;
;     if (xb) { st_bf16x4(xb + o, a); st_bf16x4(xb + o + 16, b); }
;     return ((a[0] * a[0] + a[1] * a[1]) + (a[2] * a[2] + a[3] * a[3])) + ((b[0] * b[0] + b[1] * b[1]) + (b[2] * b[2] + b[3] * b[3]));
.LBB0_389:
	v_mov_b32_e32 v134, v199
	s_add_i32 s0, s15, s28
	v_and_b32_e32 v143, 15, v134
	v_bfe_u32 v144, v134, 4, 2
	v_or_b32_e32 v134, s0, v143
	v_ashrrev_i32_e32 v135, 31, v134
	s_or_b32 s16, s33, s29
	v_lshlrev_b32_e32 v145, 2, v144
	v_lshlrev_b64 v[138:139], 11, v[134:135]
	v_or_b32_e32 v138, v138, v145
	s_ashr_i32 s17, s16, 31
	v_lshl_add_u64 v[136:137], v[138:139], 0, s[16:17]
	v_readlane_b32 s0, v253, 50
	v_lshlrev_b64 v[140:141], 2, v[136:137]
	v_readlane_b32 s1, v253, 51
	s_and_b64 vcc, exec, s[12:13]
	v_lshl_add_u64 v[136:137], v[136:137], 1, s[6:7]
	v_lshl_add_u64 v[150:151], s[0:1], 0, v[140:141]
	v_mov_b32_e32 v224, v150
	v_mov_b32_e32 v225, v151
	s_mov_b64 s[100:101], 0x20000
	global_load_dwordx4 v[152:155], v[224:225], off
	global_load_dwordx4 v[156:159], v[224:225], off offset:64
	global_load_dwordx4 v[160:163], v[224:225], off offset:512
	global_load_dwordx4 v[164:167], v[224:225], off offset:576
	v_lshl_add_u64 v[224:225], v[224:225], 0, s[100:101]
	global_load_dwordx4 v[168:171], v[224:225], off
	global_load_dwordx4 v[172:175], v[224:225], off offset:64
	global_load_dwordx4 v[176:179], v[224:225], off offset:512
	global_load_dwordx4 v[180:183], v[224:225], off offset:576
	v_lshl_add_u64 v[224:225], v[224:225], 0, s[100:101]
	global_load_dwordx4 v[184:187], v[224:225], off
	global_load_dwordx4 v[188:191], v[224:225], off offset:64
	global_load_dwordx4 v[200:203], v[224:225], off offset:512
	global_load_dwordx4 v[204:207], v[224:225], off offset:576
	v_lshl_add_u64 v[224:225], v[224:225], 0, s[100:101]
	global_load_dwordx4 v[208:211], v[224:225], off
	global_load_dwordx4 v[212:215], v[224:225], off offset:64
	global_load_dwordx4 v[216:219], v[224:225], off offset:512
	global_load_dwordx4 v[220:223], v[224:225], off offset:576
	v_lshl_add_u64 v[140:141], s[4:5], 0, v[140:141]
	s_waitcnt vmcnt(14)
	v_pk_add_f32 v[4:5], v[4:5], v[154:155]
	v_pk_add_f32 v[2:3], v[2:3], v[152:153]
	s_waitcnt vmcnt(14)
	v_pk_add_f32 v[8:9], v[8:9], v[158:159]
	v_pk_add_f32 v[6:7], v[6:7], v[156:157]
	global_store_dwordx4 v[140:141], v[2:5], off
	global_store_dwordx4 v[140:141], v[6:9], off offset:64
	s_cbranch_vccz .LBB0_391
	v_cvt_pk_bf16_f32 v146, v2, v3
	v_cvt_pk_bf16_f32 v147, v4, v5
	global_store_dwordx2 v[136:137], v[146:147], off
	v_cvt_pk_bf16_f32 v146, v6, v7
	v_cvt_pk_bf16_f32 v147, v8, v9
	global_store_dwordx2 v[136:137], v[146:147], off offset:32
.LBB0_391:
	s_or_b32 s18, s16, 0x80
	s_ashr_i32 s19, s18, 31
	v_readlane_b32 s0, v253, 50
	v_lshl_add_u64 v[138:139], v[138:139], 0, s[18:19]
	v_readlane_b32 s1, v253, 51
	v_cndmask_b32_e64 v135, 0, 1, s[12:13]
	s_andn2_b64 vcc, exec, s[12:13]
	v_lshl_add_u64 v[138:139], v[138:139], 2, s[0:1]
	v_cmp_ne_u32_e64 s[0:1], 1, v135
	s_waitcnt vmcnt(14)
	v_pk_add_f32 v[20:21], v[20:21], v[162:163]
	v_pk_add_f32 v[18:19], v[18:19], v[160:161]
	s_waitcnt vmcnt(14)
	v_pk_add_f32 v[24:25], v[24:25], v[166:167]
	v_pk_add_f32 v[22:23], v[22:23], v[164:165]
	global_store_dwordx4 v[140:141], v[18:21], off offset:512
	global_store_dwordx4 v[140:141], v[22:25], off offset:576
	s_cbranch_vccnz .LBB0_393
	v_cvt_pk_bf16_f32 v138, v18, v19
	v_cvt_pk_bf16_f32 v139, v20, v21
	global_store_dwordx2 v[136:137], v[138:139], off offset:256
	v_cvt_pk_bf16_f32 v138, v22, v23
	v_cvt_pk_bf16_f32 v139, v24, v25
	global_store_dwordx2 v[136:137], v[138:139], off offset:288
.LBB0_393:
	v_or_b32_e32 v136, 16, v134
	v_ashrrev_i32_e32 v137, 31, v136
	v_lshlrev_b64 v[136:137], 11, v[136:137]
	v_or_b32_e32 v136, v136, v145
	v_lshl_add_u64 v[146:147], v[136:137], 0, s[16:17]
	v_readlane_b32 s20, v253, 50
	v_lshlrev_b64 v[148:149], 2, v[146:147]
	v_readlane_b32 s21, v253, 51
	s_and_b64 vcc, exec, s[0:1]
	s_nop 0
	v_lshl_add_u64 v[150:151], s[20:21], 0, v[148:149]
	s_waitcnt vmcnt(14)
	v_pk_add_f32 v[36:37], v[36:37], v[170:171]
	v_pk_add_f32 v[34:35], v[34:35], v[168:169]
	s_waitcnt vmcnt(14)
	v_pk_add_f32 v[40:41], v[40:41], v[174:175]
	v_pk_add_f32 v[38:39], v[38:39], v[172:173]
	v_lshl_add_u64 v[140:141], s[4:5], 0, v[148:149]
	v_lshl_add_u64 v[138:139], v[146:147], 1, s[6:7]
	global_store_dwordx4 v[140:141], v[34:37], off
	global_store_dwordx4 v[140:141], v[38:41], off offset:64
	s_cbranch_vccnz .LBB0_395
	v_cvt_pk_bf16_f32 v146, v34, v35
	v_cvt_pk_bf16_f32 v147, v36, v37
	global_store_dwordx2 v[138:139], v[146:147], off
	v_cvt_pk_bf16_f32 v146, v38, v39
	v_cvt_pk_bf16_f32 v147, v40, v41
	global_store_dwordx2 v[138:139], v[146:147], off offset:32
.LBB0_395:
	v_readlane_b32 s20, v253, 50
	v_lshl_add_u64 v[136:137], v[136:137], 0, s[18:19]
	v_readlane_b32 s21, v253, 51
	s_and_b64 vcc, exec, s[0:1]
	s_nop 0
	v_lshl_add_u64 v[136:137], v[136:137], 2, s[20:21]
	s_waitcnt vmcnt(14)
	v_pk_add_f32 v[48:49], v[48:49], v[178:179]
	v_pk_add_f32 v[46:47], v[46:47], v[176:177]
	s_waitcnt vmcnt(14)
	v_pk_add_f32 v[52:53], v[52:53], v[182:183]
	v_pk_add_f32 v[50:51], v[50:51], v[180:181]
	global_store_dwordx4 v[140:141], v[46:49], off offset:512
	global_store_dwordx4 v[140:141], v[50:53], off offset:576
	s_cbranch_vccnz .LBB0_397
	v_cvt_pk_bf16_f32 v136, v46, v47
	v_cvt_pk_bf16_f32 v137, v48, v49
	global_store_dwordx2 v[138:139], v[136:137], off offset:256
	v_cvt_pk_bf16_f32 v136, v50, v51
	v_cvt_pk_bf16_f32 v137, v52, v53
	global_store_dwordx2 v[138:139], v[136:137], off offset:288
; DI void st_bf16x4(bf16_t* p, f32x4 v) { u32x2 o; o.x = pk2e(v[0], v[1]); o.y = pk2e(v[2], v[3]); *(u32x2*)p = o; }
;   DI float operator()(int row, int colbase, int fq, f32x4 v0, f32x4 v1) const { one(row, colbase + 4 * fq, v0); one(row, colbase + 16 + 4 * fq, v1); return 0.f; }
;   DI float operator()(int row, int colbase, int fq, f32x4 v0, f32x4 v1) const { one(row, colbase + 4 * fq, v0); one(row, colbase + 16 + 4 * fq, v1); return 0.f; }
;   DI float operator()(int row, int colbase, int fq, f32x4 v0, f32x4 v1) const { one(row, colbase + 4 * fq, v0); one(row, colbase + 16 + 4 * fq, v1); return 0.f; }
;   DI float operator()(int row, int colbase, int fq, f32x4 v0, f32x4 v1) const { one(row, colbase + 4 * fq, v0); one(row, colbase + 16 + 4 * fq, v1); return 0.f; }
;     ...
; #pragma unroll
;     for (int ai = 0; ai < 2; ++ai)
; #pragma unroll
;       for (int m = 0; m < 4; ++m) {
;         const int row = brow + ai * HALF + wr * 64 + m * 16 + fr_e;
;         const float rsc = epi.rowscale(row);
;         float ssq = 0.f;
; #pragma unroll
;         for (int bj = 0; bj < 2; ++bj)
;           ssq += epi(row, bcol + bj * HALF + wc * 32, fq_e, acc[ai][bj][m][0] * rsc, acc[ai][bj][m][1] * rsc);
;         rowss[ai][m] = ssq;
;         __builtin_amdgcn_sched_barrier(0);
;       }
;   DI float operator()(int row, int colbase, int fq, f32x4 v0, f32x4 v1) const {
;     const size_t o = (size_t)row * D_ + colbase + 4 * fq;
;     const f32x4 a = *(const f32x4*)(src + o) + v0, b = *(const f32x4*)(src + o + 16) + v1;
;     *(f32x4*)(dst + o) = a; *(f32x4*)(dst + o + 16) = b;
;     if (xb) { st_bf16x4(xb + o, a); st_bf16x4(xb + o + 16, b); }
;     return ((a[0] * a[0] + a[1] * a[1]) + (a[2] * a[2] + a[3] * a[3])) + ((b[0] * b[0] + b[1] * b[1]) + (b[2] * b[2] + b[3] * b[3]));
.LBB0_397:
	v_or_b32_e32 v136, 32, v134
	v_ashrrev_i32_e32 v137, 31, v136
	v_lshlrev_b64 v[136:137], 11, v[136:137]
	v_or_b32_e32 v136, v136, v145
	v_lshl_add_u64 v[146:147], v[136:137], 0, s[16:17]
	v_readlane_b32 s20, v253, 50
	v_lshlrev_b64 v[148:149], 2, v[146:147]
	v_readlane_b32 s21, v253, 51
	s_and_b64 vcc, exec, s[0:1]
	s_nop 0
	v_lshl_add_u64 v[150:151], s[20:21], 0, v[148:149]
	s_waitcnt vmcnt(14)
	v_pk_add_f32 v[60:61], v[60:61], v[186:187]
	v_pk_add_f32 v[58:59], v[58:59], v[184:185]
	s_waitcnt vmcnt(14)
	v_pk_add_f32 v[64:65], v[64:65], v[190:191]
	v_pk_add_f32 v[62:63], v[62:63], v[188:189]
	v_lshl_add_u64 v[140:141], s[4:5], 0, v[148:149]
	v_lshl_add_u64 v[138:139], v[146:147], 1, s[6:7]
	global_store_dwordx4 v[140:141], v[58:61], off
	global_store_dwordx4 v[140:141], v[62:65], off offset:64
	s_cbranch_vccnz .LBB0_399
	v_cvt_pk_bf16_f32 v146, v58, v59
	v_cvt_pk_bf16_f32 v147, v60, v61
	global_store_dwordx2 v[138:139], v[146:147], off
	v_cvt_pk_bf16_f32 v146, v62, v63
	v_cvt_pk_bf16_f32 v147, v64, v65
	global_store_dwordx2 v[138:139], v[146:147], off offset:32
.LBB0_399:
	v_readlane_b32 s20, v253, 50
	v_lshl_add_u64 v[136:137], v[136:137], 0, s[18:19]
	v_readlane_b32 s21, v253, 51
	s_and_b64 vcc, exec, s[0:1]
	s_nop 0
	v_lshl_add_u64 v[136:137], v[136:137], 2, s[20:21]
	s_waitcnt vmcnt(14)
	v_pk_add_f32 v[76:77], v[76:77], v[202:203]
	v_pk_add_f32 v[74:75], v[74:75], v[200:201]
	s_waitcnt vmcnt(14)
	v_pk_add_f32 v[80:81], v[80:81], v[206:207]
	v_pk_add_f32 v[78:79], v[78:79], v[204:205]
	global_store_dwordx4 v[140:141], v[74:77], off offset:512
	global_store_dwordx4 v[140:141], v[78:81], off offset:576
	s_cbranch_vccnz .LBB0_401
	v_cvt_pk_bf16_f32 v136, v74, v75
	v_cvt_pk_bf16_f32 v137, v76, v77
	global_store_dwordx2 v[138:139], v[136:137], off offset:256
	v_cvt_pk_bf16_f32 v136, v78, v79
	v_cvt_pk_bf16_f32 v137, v80, v81
	global_store_dwordx2 v[138:139], v[136:137], off offset:288
.LBB0_401:
	v_or_b32_e32 v136, 48, v134
	v_ashrrev_i32_e32 v137, 31, v136
	v_lshlrev_b64 v[136:137], 11, v[136:137]
	v_or_b32_e32 v136, v136, v145
	v_lshl_add_u64 v[146:147], v[136:137], 0, s[16:17]
	v_readlane_b32 s20, v253, 50
	v_lshlrev_b64 v[148:149], 2, v[146:147]
	v_readlane_b32 s21, v253, 51
	s_and_b64 vcc, exec, s[0:1]
	s_nop 0
	v_lshl_add_u64 v[150:151], s[20:21], 0, v[148:149]
	s_waitcnt vmcnt(14)
	v_pk_add_f32 v[92:93], v[92:93], v[210:211]
	v_pk_add_f32 v[90:91], v[90:91], v[208:209]
	s_waitcnt vmcnt(14)
	v_pk_add_f32 v[96:97], v[96:97], v[214:215]
	v_pk_add_f32 v[94:95], v[94:95], v[212:213]
	v_lshl_add_u64 v[140:141], s[4:5], 0, v[148:149]
	v_lshl_add_u64 v[138:139], v[146:147], 1, s[6:7]
	global_store_dwordx4 v[140:141], v[90:93], off
	global_store_dwordx4 v[140:141], v[94:97], off offset:64
	s_cbranch_vccnz .LBB0_403
	v_cvt_pk_bf16_f32 v146, v90, v91
	v_cvt_pk_bf16_f32 v147, v92, v93
	global_store_dwordx2 v[138:139], v[146:147], off
	v_cvt_pk_bf16_f32 v146, v94, v95
	v_cvt_pk_bf16_f32 v147, v96, v97
	global_store_dwordx2 v[138:139], v[146:147], off offset:32
.LBB0_403:
	v_readlane_b32 s20, v253, 50
	v_lshl_add_u64 v[136:137], v[136:137], 0, s[18:19]
	v_readlane_b32 s21, v253, 51
	s_and_b64 vcc, exec, s[0:1]
	s_nop 0
	v_lshl_add_u64 v[136:137], v[136:137], 2, s[20:21]
	s_waitcnt vmcnt(14)
	v_pk_add_f32 v[108:109], v[108:109], v[218:219]
	v_pk_add_f32 v[106:107], v[106:107], v[216:217]
	s_waitcnt vmcnt(14)
	v_pk_add_f32 v[112:113], v[112:113], v[222:223]
	v_pk_add_f32 v[110:111], v[110:111], v[220:221]
	s_mov_b64 s[100:101], 0xa0000
	v_lshl_add_u64 v[224:225], v[224:225], 0, s[100:101]
	s_mov_b64 s[100:101], 0x20000
	global_load_dwordx4 v[152:155], v[224:225], off
	global_load_dwordx4 v[156:159], v[224:225], off offset:64
	global_load_dwordx4 v[160:163], v[224:225], off offset:512
	global_load_dwordx4 v[164:167], v[224:225], off offset:576
	v_lshl_add_u64 v[224:225], v[224:225], 0, s[100:101]
	global_load_dwordx4 v[168:171], v[224:225], off
	global_load_dwordx4 v[172:175], v[224:225], off offset:64
	global_load_dwordx4 v[176:179], v[224:225], off offset:512
	global_load_dwordx4 v[180:183], v[224:225], off offset:576
	v_lshl_add_u64 v[224:225], v[224:225], 0, s[100:101]
	global_load_dwordx4 v[184:187], v[224:225], off
	global_load_dwordx4 v[188:191], v[224:225], off offset:64
	global_load_dwordx4 v[200:203], v[224:225], off offset:512
	global_load_dwordx4 v[204:207], v[224:225], off offset:576
	v_lshl_add_u64 v[224:225], v[224:225], 0, s[100:101]
	global_load_dwordx4 v[208:211], v[224:225], off
	global_load_dwordx4 v[212:215], v[224:225], off offset:64
	global_load_dwordx4 v[216:219], v[224:225], off offset:512
	global_load_dwordx4 v[220:223], v[224:225], off offset:576
	global_store_dwordx4 v[140:141], v[106:109], off offset:512
	global_store_dwordx4 v[140:141], v[110:113], off offset:576
	s_cbranch_vccnz .LBB0_405
	v_cvt_pk_bf16_f32 v136, v106, v107
	v_cvt_pk_bf16_f32 v137, v108, v109
	global_store_dwordx2 v[138:139], v[136:137], off offset:256
	v_cvt_pk_bf16_f32 v136, v110, v111
	v_cvt_pk_bf16_f32 v137, v112, v113
	global_store_dwordx2 v[138:139], v[136:137], off offset:288
.LBB0_405:
	v_add_u32_e32 v136, 0x80, v134
	v_ashrrev_i32_e32 v137, 31, v136
	v_lshlrev_b64 v[136:137], 11, v[136:137]
	v_or_b32_e32 v136, v136, v145
	v_lshl_add_u64 v[146:147], v[136:137], 0, s[16:17]
	v_readlane_b32 s20, v253, 50
	v_lshlrev_b64 v[148:149], 2, v[146:147]
	v_readlane_b32 s21, v253, 51
	s_and_b64 vcc, exec, s[0:1]
	s_nop 0
	v_lshl_add_u64 v[150:151], s[20:21], 0, v[148:149]
	s_waitcnt vmcnt(14)
	v_pk_add_f32 v[116:117], v[116:117], v[154:155]
	v_pk_add_f32 v[114:115], v[114:115], v[152:153]
	s_waitcnt vmcnt(14)
	v_pk_add_f32 v[120:121], v[120:121], v[158:159]
	v_pk_add_f32 v[118:119], v[118:119], v[156:157]
	v_lshl_add_u64 v[140:141], s[4:5], 0, v[148:149]
	v_lshl_add_u64 v[138:139], v[146:147], 1, s[6:7]
	global_store_dwordx4 v[140:141], v[114:117], off
	global_store_dwordx4 v[140:141], v[118:121], off offset:64
	s_cbranch_vccnz .LBB0_407
	v_cvt_pk_bf16_f32 v146, v114, v115
	v_cvt_pk_bf16_f32 v147, v116, v117
	global_store_dwordx2 v[138:139], v[146:147], off
	v_cvt_pk_bf16_f32 v146, v118, v119
	v_cvt_pk_bf16_f32 v147, v120, v121
	global_store_dwordx2 v[138:139], v[146:147], off offset:32
; DI void st_bf16x4(bf16_t* p, f32x4 v) { u32x2 o; o.x = pk2e(v[0], v[1]); o.y = pk2e(v[2], v[3]); *(u32x2*)p = o; }
;   DI float operator()(int row, int colbase, int fq, f32x4 v0, f32x4 v1) const { one(row, colbase + 4 * fq, v0); one(row, colbase + 16 + 4 * fq, v1); return 0.f; }
;   DI float operator()(int row, int colbase, int fq, f32x4 v0, f32x4 v1) const { one(row, colbase + 4 * fq, v0); one(row, colbase + 16 + 4 * fq, v1); return 0.f; }
;   DI float operator()(int row, int colbase, int fq, f32x4 v0, f32x4 v1) const { one(row, colbase + 4 * fq, v0); one(row, colbase + 16 + 4 * fq, v1); return 0.f; }
;   DI float operator()(int row, int colbase, int fq, f32x4 v0, f32x4 v1) const { one(row, colbase + 4 * fq, v0); one(row, colbase + 16 + 4 * fq, v1); return 0.f; }
;     ...
; #pragma unroll
;     for (int ai = 0; ai < 2; ++ai)
; #pragma unroll
;       for (int m = 0; m < 4; ++m) {
;         const int row = brow + ai * HALF + wr * 64 + m * 16 + fr_e;
;         const float rsc = epi.rowscale(row);
;         float ssq = 0.f;
; #pragma unroll
;         for (int bj = 0; bj < 2; ++bj)
;           ssq += epi(row, bcol + bj * HALF + wc * 32, fq_e, acc[ai][bj][m][0] * rsc, acc[ai][bj][m][1] * rsc);
;         rowss[ai][m] = ssq;
;         __builtin_amdgcn_sched_barrier(0);
;       }
;   DI float operator()(int row, int colbase, int fq, f32x4 v0, f32x4 v1) const {
;     const size_t o = (size_t)row * D_ + colbase + 4 * fq;
;     const f32x4 a = *(const f32x4*)(src + o) + v0, b = *(const f32x4*)(src + o + 16) + v1;
;     *(f32x4*)(dst + o) = a; *(f32x4*)(dst + o + 16) = b;
;     if (xb) { st_bf16x4(xb + o, a); st_bf16x4(xb + o + 16, b); }
;     return ((a[0] * a[0] + a[1] * a[1]) + (a[2] * a[2] + a[3] * a[3])) + ((b[0] * b[0] + b[1] * b[1]) + (b[2] * b[2] + b[3] * b[3]));
.LBB0_407:
	v_readlane_b32 s20, v253, 50
	v_lshl_add_u64 v[136:137], v[136:137], 0, s[18:19]
	v_readlane_b32 s21, v253, 51
	s_and_b64 vcc, exec, s[0:1]
	s_nop 0
	v_lshl_add_u64 v[136:137], v[136:137], 2, s[20:21]
	s_waitcnt vmcnt(14)
	v_pk_add_f32 v[128:129], v[128:129], v[162:163]
	v_pk_add_f32 v[126:127], v[126:127], v[160:161]
	s_waitcnt vmcnt(14)
	v_pk_add_f32 v[124:125], v[124:125], v[166:167]
	v_pk_add_f32 v[122:123], v[122:123], v[164:165]
	global_store_dwordx4 v[140:141], v[126:129], off offset:512
	global_store_dwordx4 v[140:141], v[122:125], off offset:576
	s_cbranch_vccnz .LBB0_409
	v_cvt_pk_bf16_f32 v136, v126, v127
	v_cvt_pk_bf16_f32 v137, v128, v129
	global_store_dwordx2 v[138:139], v[136:137], off offset:256
	v_cvt_pk_bf16_f32 v136, v122, v123
	v_cvt_pk_bf16_f32 v137, v124, v125
	global_store_dwordx2 v[138:139], v[136:137], off offset:288
.LBB0_409:
	v_add_u32_e32 v136, 0x90, v134
	v_ashrrev_i32_e32 v137, 31, v136
	v_lshlrev_b64 v[136:137], 11, v[136:137]
	v_or_b32_e32 v136, v136, v145
	v_lshl_add_u64 v[146:147], v[136:137], 0, s[16:17]
	v_readlane_b32 s20, v253, 50
	v_lshlrev_b64 v[148:149], 2, v[146:147]
	v_readlane_b32 s21, v253, 51
	s_and_b64 vcc, exec, s[0:1]
	s_nop 0
	v_lshl_add_u64 v[150:151], s[20:21], 0, v[148:149]
	s_waitcnt vmcnt(14)
	v_pk_add_f32 v[104:105], v[104:105], v[170:171]
	v_pk_add_f32 v[102:103], v[102:103], v[168:169]
	s_waitcnt vmcnt(14)
	v_pk_add_f32 v[100:101], v[100:101], v[174:175]
	v_pk_add_f32 v[98:99], v[98:99], v[172:173]
	v_lshl_add_u64 v[140:141], s[4:5], 0, v[148:149]
	v_lshl_add_u64 v[138:139], v[146:147], 1, s[6:7]
	global_store_dwordx4 v[140:141], v[102:105], off
	global_store_dwordx4 v[140:141], v[98:101], off offset:64
	s_cbranch_vccnz .LBB0_411
	v_cvt_pk_bf16_f32 v146, v102, v103
	v_cvt_pk_bf16_f32 v147, v104, v105
	global_store_dwordx2 v[138:139], v[146:147], off
	v_cvt_pk_bf16_f32 v146, v98, v99
	v_cvt_pk_bf16_f32 v147, v100, v101
	global_store_dwordx2 v[138:139], v[146:147], off offset:32
.LBB0_411:
	v_readlane_b32 s20, v253, 50
	v_lshl_add_u64 v[136:137], v[136:137], 0, s[18:19]
	v_readlane_b32 s21, v253, 51
	s_and_b64 vcc, exec, s[0:1]
	s_nop 0
	v_lshl_add_u64 v[136:137], v[136:137], 2, s[20:21]
	s_waitcnt vmcnt(14)
	v_pk_add_f32 v[88:89], v[88:89], v[178:179]
	v_pk_add_f32 v[86:87], v[86:87], v[176:177]
	s_waitcnt vmcnt(14)
	v_pk_add_f32 v[84:85], v[84:85], v[182:183]
	v_pk_add_f32 v[82:83], v[82:83], v[180:181]
	global_store_dwordx4 v[140:141], v[86:89], off offset:512
	global_store_dwordx4 v[140:141], v[82:85], off offset:576
	s_cbranch_vccnz .LBB0_413
	v_cvt_pk_bf16_f32 v136, v86, v87
	v_cvt_pk_bf16_f32 v137, v88, v89
	global_store_dwordx2 v[138:139], v[136:137], off offset:256
	v_cvt_pk_bf16_f32 v136, v82, v83
	v_cvt_pk_bf16_f32 v137, v84, v85
	global_store_dwordx2 v[138:139], v[136:137], off offset:288
.LBB0_413:
	v_add_u32_e32 v136, 0xa0, v134
	v_ashrrev_i32_e32 v137, 31, v136
	v_lshlrev_b64 v[136:137], 11, v[136:137]
	v_or_b32_e32 v136, v136, v145
	v_lshl_add_u64 v[146:147], v[136:137], 0, s[16:17]
	v_readlane_b32 s20, v253, 50
	v_lshlrev_b64 v[148:149], 2, v[146:147]
	v_readlane_b32 s21, v253, 51
	s_and_b64 vcc, exec, s[0:1]
	s_nop 0
	v_lshl_add_u64 v[150:151], s[20:21], 0, v[148:149]
	s_waitcnt vmcnt(14)
	v_pk_add_f32 v[72:73], v[72:73], v[186:187]
	v_pk_add_f32 v[70:71], v[70:71], v[184:185]
	s_waitcnt vmcnt(14)
	v_pk_add_f32 v[68:69], v[68:69], v[190:191]
	v_pk_add_f32 v[66:67], v[66:67], v[188:189]
	v_lshl_add_u64 v[140:141], s[4:5], 0, v[148:149]
	v_lshl_add_u64 v[138:139], v[146:147], 1, s[6:7]
	global_store_dwordx4 v[140:141], v[70:73], off
	global_store_dwordx4 v[140:141], v[66:69], off offset:64
	s_cbranch_vccnz .LBB0_415
	v_cvt_pk_bf16_f32 v146, v70, v71
	v_cvt_pk_bf16_f32 v147, v72, v73
	global_store_dwordx2 v[138:139], v[146:147], off
	v_cvt_pk_bf16_f32 v146, v66, v67
	v_cvt_pk_bf16_f32 v147, v68, v69
	global_store_dwordx2 v[138:139], v[146:147], off offset:32
.LBB0_415:
	v_readlane_b32 s20, v253, 50
	v_lshl_add_u64 v[136:137], v[136:137], 0, s[18:19]
	v_readlane_b32 s21, v253, 51
	s_and_b64 vcc, exec, s[0:1]
	s_nop 0
	v_lshl_add_u64 v[136:137], v[136:137], 2, s[20:21]
	s_waitcnt vmcnt(14)
	v_pk_add_f32 v[56:57], v[56:57], v[202:203]
	v_pk_add_f32 v[54:55], v[54:55], v[200:201]
	s_waitcnt vmcnt(14)
	v_pk_add_f32 v[44:45], v[44:45], v[206:207]
	v_pk_add_f32 v[42:43], v[42:43], v[204:205]
	global_store_dwordx4 v[140:141], v[54:57], off offset:512
	global_store_dwordx4 v[140:141], v[42:45], off offset:576
	s_cbranch_vccnz .LBB0_417
	v_cvt_pk_bf16_f32 v136, v54, v55
	v_cvt_pk_bf16_f32 v137, v56, v57
	global_store_dwordx2 v[138:139], v[136:137], off offset:256
	v_cvt_pk_bf16_f32 v136, v42, v43
	v_cvt_pk_bf16_f32 v137, v44, v45
	global_store_dwordx2 v[138:139], v[136:137], off offset:288
.LBB0_417:
	v_add_u32_e32 v134, 0xb0, v134
	v_ashrrev_i32_e32 v135, 31, v134
	v_lshlrev_b64 v[134:135], 11, v[134:135]
	v_or_b32_e32 v134, v134, v145
	v_lshl_add_u64 v[140:141], v[134:135], 0, s[16:17]
	v_readlane_b32 s16, v253, 50
	v_lshlrev_b64 v[146:147], 2, v[140:141]
	v_readlane_b32 s17, v253, 51
	s_and_b64 vcc, exec, s[0:1]
	s_nop 0
	v_lshl_add_u64 v[148:149], s[16:17], 0, v[146:147]
	s_waitcnt vmcnt(14)
	v_pk_add_f32 v[32:33], v[32:33], v[210:211]
	v_pk_add_f32 v[30:31], v[30:31], v[208:209]
	s_waitcnt vmcnt(14)
	v_pk_add_f32 v[28:29], v[28:29], v[214:215]
	v_pk_add_f32 v[26:27], v[26:27], v[212:213]
	v_lshl_add_u64 v[138:139], s[4:5], 0, v[146:147]
	v_lshl_add_u64 v[136:137], v[140:141], 1, s[6:7]
	global_store_dwordx4 v[138:139], v[30:33], off
	global_store_dwordx4 v[138:139], v[26:29], off offset:64
	s_cbranch_vccnz .LBB0_419
	v_cvt_pk_bf16_f32 v140, v30, v31
	v_cvt_pk_bf16_f32 v141, v32, v33
	global_store_dwordx2 v[136:137], v[140:141], off
	v_cvt_pk_bf16_f32 v140, v26, v27
	v_cvt_pk_bf16_f32 v141, v28, v29
	global_store_dwordx2 v[136:137], v[140:141], off offset:32
.LBB0_419:
	v_readlane_b32 s16, v253, 50
	v_lshl_add_u64 v[134:135], v[134:135], 0, s[18:19]
	v_readlane_b32 s17, v253, 51
	s_and_b64 vcc, exec, s[0:1]
	s_nop 0
	v_lshl_add_u64 v[134:135], v[134:135], 2, s[16:17]
	s_waitcnt vmcnt(14)
	v_pk_add_f32 v[16:17], v[16:17], v[218:219]
	v_pk_add_f32 v[14:15], v[14:15], v[216:217]
	s_waitcnt vmcnt(14)
	v_pk_add_f32 v[12:13], v[12:13], v[222:223]
	v_pk_add_f32 v[10:11], v[10:11], v[220:221]
	global_store_dwordx4 v[138:139], v[14:17], off offset:512
	global_store_dwordx4 v[138:139], v[10:13], off offset:576
	s_cbranch_vccnz .LBB0_421
	v_cvt_pk_bf16_f32 v134, v14, v15
	v_cvt_pk_bf16_f32 v135, v16, v17
	global_store_dwordx2 v[136:137], v[134:135], off offset:256
	v_cvt_pk_bf16_f32 v134, v10, v11
	v_cvt_pk_bf16_f32 v135, v12, v13
	global_store_dwordx2 v[136:137], v[134:135], off offset:288

; #define LAS __attribute__((address_space(3)))
; __global__ void __launch_bounds__(NTH) fwd_megakernel(Params p) {
;     ...
;   cg::grid_group grid = cg::this_grid();
;   extern __shared__ __attribute__((aligned(16))) char dyn_lds[];
;   volatile LAS unsigned* xst = (volatile LAS unsigned*)((LAS unsigned char*)dyn_lds + NSA_LDS);
;   if (threadIdx.x == 0) { xst[0] = 0u; xst[1] = 0u; xst[2] = 0u; xst[3] = 0u; }
;   __syncthreads();
;   const XcdBarrier xb = xcd_barrier_post((unsigned*)(p.ws + A_BAR), xst);
;   for (int ph = p.ph_lo; ph < p.ph_hi; ++ph) {
;     if (ph >= PH_PRE && (((ph - PH_PRE) / PH_PER_LAYER) & 1) == 1 && (ph - PH_PRE) % PH_PER_LAYER == 3) continue;
;     run_phase(p, ph);
;     if (ph + 1 < p.ph_hi) { if (ph == 0) grid.sync(); else xcd_barrier(xb); }
;   }
;     ...
;   for (int ph = p.ph_lo; ph < p.ph_hi; ++ph) run_phase(p, ph);
;     ...
; }
	.amdhsa_kernel _Z14fwd_megakernel6Params
		.amdhsa_group_segment_fixed_size 0
		.amdhsa_private_segment_fixed_size 0
		.amdhsa_kernarg_size 528
		.amdhsa_user_sgpr_count 2
		.amdhsa_user_sgpr_dispatch_ptr 0
		.amdhsa_user_sgpr_queue_ptr 0
		.amdhsa_user_sgpr_kernarg_segment_ptr 1
		.amdhsa_user_sgpr_dispatch_id 0
		.amdhsa_user_sgpr_kernarg_preload_length 0
		.amdhsa_user_sgpr_kernarg_preload_offset 0
		.amdhsa_user_sgpr_private_segment_size 0
		.amdhsa_uses_dynamic_stack 0
		.amdhsa_enable_private_segment 0
		.amdhsa_system_sgpr_workgroup_id_x 1
		.amdhsa_system_sgpr_workgroup_id_y 0
		.amdhsa_system_sgpr_workgroup_id_z 0
		.amdhsa_system_sgpr_workgroup_info 0
		.amdhsa_system_vgpr_workitem_id 2
		.amdhsa_next_free_vgpr 256
		.amdhsa_next_free_sgpr 102
		.amdhsa_accum_offset 256
		.amdhsa_reserve_vcc 1
		.amdhsa_float_round_mode_32 0
		.amdhsa_float_round_mode_16_64 0
		.amdhsa_float_denorm_mode_32 3
		.amdhsa_float_denorm_mode_16_64 3
		.amdhsa_dx10_clamp 1
		.amdhsa_ieee_mode 1
		.amdhsa_fp16_overflow 0
		.amdhsa_tg_split 0
		.amdhsa_exception_fp_ieee_invalid_op 0
		.amdhsa_exception_fp_denorm_src 0
		.amdhsa_exception_fp_ieee_div_zero 0
		.amdhsa_exception_fp_ieee_overflow 0
		.amdhsa_exception_fp_ieee_underflow 0
		.amdhsa_exception_fp_ieee_inexact 0
		.amdhsa_exception_int_div_zero 0
	.end_amdhsa_kernel

; #define LAS __attribute__((address_space(3)))
; __global__ void __launch_bounds__(NTH) fwd_megakernel(Params p) {
;     ...
;   cg::grid_group grid = cg::this_grid();
;   extern __shared__ __attribute__((aligned(16))) char dyn_lds[];
;   volatile LAS unsigned* xst = (volatile LAS unsigned*)((LAS unsigned char*)dyn_lds + NSA_LDS);
;   if (threadIdx.x == 0) { xst[0] = 0u; xst[1] = 0u; xst[2] = 0u; xst[3] = 0u; }
;   __syncthreads();
;   const XcdBarrier xb = xcd_barrier_post((unsigned*)(p.ws + A_BAR), xst);
;   for (int ph = p.ph_lo; ph < p.ph_hi; ++ph) {
;     if (ph >= PH_PRE && (((ph - PH_PRE) / PH_PER_LAYER) & 1) == 1 && (ph - PH_PRE) % PH_PER_LAYER == 3) continue;
;     run_phase(p, ph);
;     if (ph + 1 < p.ph_hi) { if (ph == 0) grid.sync(); else xcd_barrier(xb); }
;   }
;     ...
;   for (int ph = p.ph_lo; ph < p.ph_hi; ++ph) run_phase(p, ph);
;     ...
; }
amdhsa.kernels:
  - .agpr_count:     0
    .args:
      - .offset:         0
        .size:           272
        .value_kind:     by_value
      - .offset:         272
        .size:           4
        .value_kind:     hidden_block_count_x
      - .offset:         276
        .size:           4
        .value_kind:     hidden_block_count_y
      - .offset:         280
        .size:           4
        .value_kind:     hidden_block_count_z
      - .offset:         284
        .size:           2
        .value_kind:     hidden_group_size_x
      - .offset:         286
        .size:           2
        .value_kind:     hidden_group_size_y
      - .offset:         288
        .size:           2
        .value_kind:     hidden_group_size_z
      - .offset:         290
        .size:           2
        .value_kind:     hidden_remainder_x
      - .offset:         292
        .size:           2
        .value_kind:     hidden_remainder_y
      - .offset:         294
        .size:           2
        .value_kind:     hidden_remainder_z
      - .offset:         312
        .size:           8
        .value_kind:     hidden_global_offset_x
      - .offset:         320
        .size:           8
        .value_kind:     hidden_global_offset_y
      - .offset:         328
        .size:           8
        .value_kind:     hidden_global_offset_z
      - .offset:         336
        .size:           2
        .value_kind:     hidden_grid_dims
      - .offset:         360
        .size:           8
        .value_kind:     hidden_multigrid_sync_arg
      - .offset:         392
        .size:           4
        .value_kind:     hidden_dynamic_lds_size
    .group_segment_fixed_size: 0
    .kernarg_segment_align: 8
    .kernarg_segment_size: 528
    .language:       OpenCL C
    .language_version:
      - 2
      - 0
    .max_flat_workgroup_size: 512
    .name:           _Z14fwd_megakernel6Params
    .private_segment_fixed_size: 0
    .sgpr_count:     108
    .sgpr_spill_count: 395
    .symbol:         _Z14fwd_megakernel6Params.kd
    .uniform_work_group_size: 1
    .uses_dynamic_stack: false
    .vgpr_count:     256
    .vgpr_spill_count: 0
    .wavefront_size: 64
